# grid barrier: XCD leaders also poll the arrival counter directly and issue their acquire invalidate right after arriving
# baseline (speedup 1.0000x reference)
; __device__ __forceinline__ unsigned xb_ld(unsigned* p)              { return __hip_atomic_load(p, __ATOMIC_RELAXED, __HIP_MEMORY_SCOPE_AGENT); }
; __device__ __forceinline__ unsigned xb_add(unsigned* p, unsigned v) { return __hip_atomic_fetch_add(p, v, __ATOMIC_RELAXED, __HIP_MEMORY_SCOPE_AGENT); }
; #define XB_SPIN(cond, bar) do { unsigned _sp = 0; while (cond) { __builtin_amdgcn_s_sleep(1); \
;     if ((++_sp & 255u) == 0u) { if (xb_ld(&(bar)[XB_TMO])) break; if (_sp > XB_SPIN_CAP) { atomicAdd(&(bar)[XB_TMO], 1u); break; } } } } while (0)
; __device__ __forceinline__ void xcd_barrier(const XcdBarrier& b) {
;     ...
;             const unsigned og = xb_add(&bar[XB_TOP], 1u);
;             const unsigned tg = og / nx;
;             if (og + 1u == (tg + 1u) * nx) xb_add(&bar[XB_TOPGEN], 1u);
;             else XB_SPIN(xb_ld(&bar[XB_TOPGEN]) == tg, bar);
;             __builtin_amdgcn_fence(__ATOMIC_ACQUIRE, "agent");
.LBB0_159:
	s_or_b64 exec, exec, s[8:9]
	v_cvt_f32_u32_e32 v4, v1
	buffer_inv sc1
	s_waitcnt vmcnt(1)
	v_readfirstlane_b32 s6, v3
	s_add_u32 s8, s2, 0x2e403500
	s_addc_u32 s9, s3, 0
	v_rcp_iflag_f32_e32 v4, v4
	v_add_u32_e32 v2, s6, v2
	v_add_u32_e32 v5, 1, v2
	s_mov_b64 s[10:11], -1
	v_mul_f32_e32 v3, 0x4f7ffffe, v4
	v_cvt_u32_f32_e32 v3, v3
	v_sub_u32_e32 v4, 0, v1
	v_mul_lo_u32 v4, v4, v3
	v_mul_hi_u32 v4, v3, v4
	v_add_u32_e32 v3, v3, v4
	v_mul_hi_u32 v3, v2, v3
	v_mul_lo_u32 v4, v3, v1
	v_sub_u32_e32 v2, v2, v4
	v_add_u32_e32 v6, 1, v3
	v_cmp_ge_u32_e32 vcc, v2, v1
	v_sub_u32_e32 v4, v2, v1
	s_nop 0
	v_cndmask_b32_e32 v3, v3, v6, vcc
	v_cndmask_b32_e32 v2, v2, v4, vcc
	v_add_u32_e32 v4, 1, v3
	v_cmp_ge_u32_e32 vcc, v2, v1
	s_nop 1
	v_cndmask_b32_e32 v4, v3, v4, vcc
	v_mul_lo_u32 v2, v1, v4
	v_add_u32_e32 v1, v2, v1
	v_cmp_ne_u32_e32 vcc, v5, v1
	v_mov_b32_e32 v4, v1
	v_mov_b64_e32 v[2:3], s[8:9]
	s_and_saveexec_b64 s[6:7], vcc
	s_cbranch_execz .LBB0_171
	v_mov_b32_e32 v1, 0
	global_load_dword v2, v1, s[8:9] offset:-256 sc1
	s_mov_b64 s[14:15], 0
	s_waitcnt vmcnt(0)
	v_cmp_lt_u32_e32 vcc, v2, v4
	s_and_saveexec_b64 s[12:13], vcc
	s_cbranch_execz .LBB0_170
	s_add_u32 s10, s2, 0x2e400200
	s_addc_u32 s11, s3, 0
	s_mov_b32 s22, 1
	s_mov_b64 s[2:3], 0
	s_branch .LBB0_163

; __device__ __forceinline__ unsigned xb_ld(unsigned* p)              { return __hip_atomic_load(p, __ATOMIC_RELAXED, __HIP_MEMORY_SCOPE_AGENT); }
; #define XB_SPIN(cond, bar) do { unsigned _sp = 0; while (cond) { __builtin_amdgcn_s_sleep(1); \
;     if ((++_sp & 255u) == 0u) { if (xb_ld(&(bar)[XB_TMO])) break; if (_sp > XB_SPIN_CAP) { atomicAdd(&(bar)[XB_TMO], 1u); break; } } } } while (0)
; __device__ __forceinline__ void xcd_barrier(const XcdBarrier& b) {
;     ...
;             else XB_SPIN(xb_ld(&bar[XB_TOPGEN]) == tg, bar);
.LBB0_165:
	global_load_dword v2, v1, s[8:9] offset:-256 sc1
	s_add_i32 s22, s22, 1
	s_mov_b64 s[16:17], -1
	s_waitcnt vmcnt(0)
	v_cmp_ge_u32_e32 vcc, v2, v4
	s_orn2_b64 s[20:21], vcc, exec
	s_branch .LBB0_162

; __device__ __forceinline__ unsigned xb_add(unsigned* p, unsigned v) { return __hip_atomic_fetch_add(p, v, __ATOMIC_RELAXED, __HIP_MEMORY_SCOPE_AGENT); }
; __device__ __forceinline__ void xcd_barrier(const XcdBarrier& b) {
;     ...
;             __builtin_amdgcn_fence(__ATOMIC_ACQUIRE, "agent");
;             xb_add(&bar[XB_XGEN(b.x)], 1u);
;             asm volatile("s_waitcnt vmcnt(0)" ::: "memory");
.LBB0_173:
	s_or_b64 exec, exec, s[2:3]
	s_mov_b64 s[2:3], exec
	v_mbcnt_lo_u32_b32 v1, s2, 0
	v_mbcnt_hi_u32_b32 v1, s3, v1
	v_cmp_eq_u32_e32 vcc, 0, v1
	s_waitcnt vmcnt(0)
	s_and_saveexec_b64 s[6:7], vcc
	s_cbranch_execz .LBB0_175
	s_bcnt1_i32_b64 s2, s[2:3]
	v_mov_b32_e32 v1, 0x2000
	v_mov_b32_e32 v2, s2
	global_atomic_add v1, v2, s[4:5] offset:1024

; #define PG8_STAGE(bufoff, gbase, voff) do { _Pragma("unroll") for (int _i = 0; _i < 2; ++_i) \
;         __builtin_amdgcn_global_load_lds((const unsigned*)((const char*)(gbase) + (voff)[_i]), (PG8_LAS unsigned*)(lds + (bufoff) + ldsw + _i * 8192), 16, 0, 0); } while (0)
; #define PG8_LDA(dst, b, h) do { _Pragma("unroll") for (int m = 0; m < 4; ++m) _Pragma("unroll") for (int k = 0; k < 2; ++k) dst[m][k] = *(const PG8_LAS bf16x8*)(lds + PG8_SA(b, h) + aoff + m * 2048 + k * 1024); } while (0)
; #define PG8_LDB(dst, b, h) do { _Pragma("unroll") for (int n = 0; n < 2; ++n) _Pragma("unroll") for (int k = 0; k < 2; ++k) dst[n][k] = *(const PG8_LAS bf16x8*)(lds + PG8_SB(b, h) + boff + n * 2048 + k * 1024); } while (0)
; #define PG8_MMA(ai, bj, At, Bt) do { __builtin_amdgcn_s_setprio(1); _Pragma("unroll") for (int m = 0; m < 4; ++m) _Pragma("unroll") for (int n = 0; n < 2; ++n) _Pragma("unroll") for (int k = 0; k < 2; ++k) \
;         acc[ai][bj][m][n] = __builtin_amdgcn_mfma_f32_16x16x32_bf16(Bt[n][k], At[m][k], acc[ai][bj][m][n], 0, 0, 0); __builtin_amdgcn_s_setprio(0); } while (0)
; #define PG8_WAIT_V(n) asm volatile("s_waitcnt vmcnt(" #n ")" ::: "memory")
; #define PG8_WAIT_L(n) asm volatile("s_waitcnt lgkmcnt(" #n ")" ::: "memory")
; template <class Epi, class Sched, bool ALIGN_EPI = false, bool SP2 = false>
; __device__ __forceinline__ void gemm_phase(PG8_LAS unsigned char* lds, const Gemm g, const Sched& S, const Epi& E) {
;     ...
;     for (;;) {
;         const bool has_next = S.next(ui + 1, nxt);
;         const char* nA = has_next ? (const char*)g.A + (size_t)nxt.pm * tstep : cA; const char* nB = has_next ? (const char*)g.Bt + (size_t)nxt.pn * tstep : cB;
;         for (int t = 0; t < nt; t += 2) {
;             const bool last = (t == nt - 2);
;             const char* a1 = cA + (size_t)(t + 1) * kstep;
;             const char* a2 = last ? nA : cA + (size_t)(t + 2) * kstep; const char* b2 = last ? nB : cB + (size_t)(t + 2) * kstep;
;             const char* a3 = a2 + kstep; const char* b3 = b2 + kstep;
;             if (last && has_next) S.a_ready(nxt);
;             if constexpr (SP2) {
;             PG8_LDB(B0, 0, 0); PG8_LDB(B1, 0, 1); PG8_SCHED; PG8_LDA(At, 0, 0); PG8_STAGE(PG8_SA(1, 1), a1 + hstep, voffA);
;             PG8_WAIT_V(8); PG8_WAIT_L(0); PG8_BAR; PG8_MMA(0, 0, At, B0); PG8_MMA(0, 1, At, B1); PG8_BAR; PG8_SCHED;
.LBB0_220:
	s_ashr_i32 s25, s24, 31
	s_lshl_b64 s[2:3], s[24:25], 20
	s_add_u32 s2, s12, s2
	s_addc_u32 s3, s13, s3
	s_and_b64 s[26:27], s[8:9], exec
	s_cselect_b32 s25, s3, s1
	s_cselect_b32 s46, s2, s0
	s_ashr_i32 s23, s22, 31
	s_lshl_b64 s[26:27], s[22:23], 20
	s_add_u32 s26, s31, s26
	s_addc_u32 s27, s34, s27
	s_and_b64 s[28:29], s[8:9], exec
	s_cselect_b32 s23, s27, s5
	s_cselect_b32 s47, s26, s4
	s_add_u32 s0, s0, 0x80080
	s_addc_u32 s1, s1, 0
	s_add_u32 s48, s4, 0x100
	v_mov_b32_e32 v0, 0
	s_addc_u32 s49, s5, 0
	s_mov_b32 s50, -2
	v_mov_b32_e32 v1, v0
	s_waitcnt lgkmcnt(0)
	v_mov_b32_e32 v2, v0
	v_mov_b32_e32 v3, v0
	v_mov_b32_e32 v4, v0
	v_mov_b32_e32 v5, v0
	v_mov_b32_e32 v6, v0
	v_mov_b32_e32 v7, v0
	v_mov_b32_e32 v16, v0
	v_mov_b32_e32 v17, v0
	s_waitcnt vmcnt(0)
	v_mov_b32_e32 v18, v0
	v_mov_b32_e32 v19, v0
	v_mov_b32_e32 v20, v0
	v_mov_b32_e32 v21, v0
	v_mov_b32_e32 v22, v0
	v_mov_b32_e32 v23, v0
	v_mov_b32_e32 v32, v0
	v_mov_b32_e32 v33, v0
	v_mov_b32_e32 v34, v0
	v_mov_b32_e32 v35, v0
	v_mov_b32_e32 v36, v0
	v_mov_b32_e32 v37, v0
	v_mov_b32_e32 v38, v0
	v_mov_b32_e32 v39, v0
	v_mov_b32_e32 v48, v0
	v_mov_b32_e32 v49, v0
	v_mov_b32_e32 v50, v0
	v_mov_b32_e32 v51, v0
	v_mov_b32_e32 v52, v0
	v_mov_b32_e32 v53, v0
	v_mov_b32_e32 v54, v0
	v_mov_b32_e32 v55, v0
	v_mov_b32_e32 v8, v0
	v_mov_b32_e32 v9, v0
	v_mov_b32_e32 v10, v0
	v_mov_b32_e32 v11, v0
	v_mov_b32_e32 v12, v0
	v_mov_b32_e32 v13, v0
	v_mov_b32_e32 v14, v0
	v_mov_b32_e32 v15, v0
	v_mov_b32_e32 v24, v0
	v_mov_b32_e32 v25, v0
	v_mov_b32_e32 v26, v0
	v_mov_b32_e32 v27, v0
	v_mov_b32_e32 v28, v0
	v_mov_b32_e32 v29, v0
	v_mov_b32_e32 v30, v0
	v_mov_b32_e32 v31, v0
	v_mov_b32_e32 v40, v0
	v_mov_b32_e32 v41, v0
	v_mov_b32_e32 v42, v0
	v_mov_b32_e32 v43, v0
	v_mov_b32_e32 v44, v0
	v_mov_b32_e32 v45, v0
	v_mov_b32_e32 v46, v0
	v_mov_b32_e32 v47, v0
	v_mov_b32_e32 v56, v0
	v_mov_b32_e32 v57, v0
	v_mov_b32_e32 v58, v0
	v_mov_b32_e32 v59, v0
	v_mov_b32_e32 v60, v0
	v_mov_b32_e32 v61, v0
	v_mov_b32_e32 v62, v0
	v_mov_b32_e32 v63, v0
	v_mov_b32_e32 v64, v0
	v_mov_b32_e32 v65, v0
	v_mov_b32_e32 v66, v0
	v_mov_b32_e32 v67, v0
	v_mov_b32_e32 v68, v0
	v_mov_b32_e32 v69, v0
	v_mov_b32_e32 v70, v0
	v_mov_b32_e32 v71, v0
	v_mov_b32_e32 v80, v0
	v_mov_b32_e32 v81, v0
	v_mov_b32_e32 v82, v0
	v_mov_b32_e32 v83, v0
	v_mov_b32_e32 v84, v0
	v_mov_b32_e32 v85, v0
	v_mov_b32_e32 v86, v0
	v_mov_b32_e32 v87, v0
	v_mov_b32_e32 v96, v0
	v_mov_b32_e32 v97, v0
	v_mov_b32_e32 v98, v0
	v_mov_b32_e32 v99, v0
	v_mov_b32_e32 v100, v0
	v_mov_b32_e32 v101, v0
	v_mov_b32_e32 v102, v0
	v_mov_b32_e32 v103, v0
	v_mov_b32_e32 v112, v0
	v_mov_b32_e32 v113, v0
	v_mov_b32_e32 v114, v0
	v_mov_b32_e32 v115, v0
	v_mov_b32_e32 v116, v0
	v_mov_b32_e32 v117, v0
	v_mov_b32_e32 v118, v0
	v_mov_b32_e32 v119, v0
	v_mov_b32_e32 v72, v0
	v_mov_b32_e32 v73, v0
	v_mov_b32_e32 v74, v0
	v_mov_b32_e32 v75, v0
	v_mov_b32_e32 v76, v0
	v_mov_b32_e32 v77, v0
	v_mov_b32_e32 v78, v0
	v_mov_b32_e32 v79, v0
	v_mov_b32_e32 v88, v0
	v_mov_b32_e32 v89, v0
	v_mov_b32_e32 v90, v0
	v_mov_b32_e32 v91, v0
	v_mov_b32_e32 v92, v0
	v_mov_b32_e32 v93, v0
	v_mov_b32_e32 v94, v0
	v_mov_b32_e32 v95, v0
	v_mov_b32_e32 v104, v0
	v_mov_b32_e32 v105, v0
	v_mov_b32_e32 v106, v0
	v_mov_b32_e32 v107, v0
	v_mov_b32_e32 v108, v0
	v_mov_b32_e32 v109, v0
	v_mov_b32_e32 v110, v0
	v_mov_b32_e32 v111, v0
	v_mov_b32_e32 v120, v0
	v_mov_b32_e32 v121, v0
	v_mov_b32_e32 v122, v0
	v_mov_b32_e32 v123, v0
	v_mov_b32_e32 v124, v0
	v_mov_b32_e32 v125, v0
	v_mov_b32_e32 v126, v0
	v_mov_b32_e32 v127, v0
	s_nop 0
	s_nop 0
	s_nop 0
	s_nop 0
	s_nop 0
	s_nop 0
	s_nop 0
	s_nop 0
	s_nop 0
	s_nop 0
	s_nop 0
	s_nop 0
.LBB0_221:
	s_add_u32 s4, s0, 0xfff80080
	s_addc_u32 s5, s1, -1
	s_add_i32 s51, 0, 0x10000
	s_cmp_eq_u32 s50, 28
	s_cselect_b32 s29, s25, s5
	s_cselect_b32 s28, s46, s4
	v_add_u32_e32 v146, s51, v150
	s_cselect_b32 s5, s23, s49
	s_cselect_b32 s4, s47, s48
	s_add_i32 s54, 0, 0x14000
	ds_read_b128 v[138:141], v146
	ds_read_b128 v[142:145], v146 offset:1024
	ds_read_b128 v[164:167], v146 offset:2048
	ds_read_b128 v[168:171], v146 offset:3072
	v_add_u32_e32 v146, s54, v150
	ds_read_b128 v[172:175], v146
	ds_read_b128 v[176:179], v146 offset:1024
	ds_read_b128 v[180:183], v146 offset:2048
	ds_read_b128 v[184:187], v146 offset:3072
	v_lshl_add_u64 v[146:147], s[0:1], 0, v[134:135]
	s_add_i32 m0, s35, 0xc000
	ds_read_b128 v[188:191], v151
	ds_read_b128 v[192:195], v151 offset:1024
	ds_read_b128 v[196:199], v151 offset:2048
	ds_read_b128 v[200:203], v151 offset:3072
	ds_read_b128 v[204:207], v151 offset:4096
	ds_read_b128 v[208:211], v151 offset:5120
	ds_read_b128 v[212:215], v151 offset:6144
	ds_read_b128 v[216:219], v151 offset:7168
	global_load_lds_dwordx4 v[146:147], off
	v_lshl_add_u64 v[146:147], s[0:1], 0, v[136:137]
	s_add_i32 m0, s35, 0xe000
	s_nop 0
	global_load_lds_dwordx4 v[146:147], off
	s_waitcnt vmcnt(8)
	s_waitcnt lgkmcnt(0)
	s_setprio 1
	s_barrier
; #define PG8_STAGE(bufoff, gbase, voff) do { _Pragma("unroll") for (int _i = 0; _i < 2; ++_i) \
;         __builtin_amdgcn_global_load_lds((const unsigned*)((const char*)(gbase) + (voff)[_i]), (PG8_LAS unsigned*)(lds + (bufoff) + ldsw + _i * 8192), 16, 0, 0); } while (0)
; #define PG8_LDA(dst, b, h) do { _Pragma("unroll") for (int m = 0; m < 4; ++m) _Pragma("unroll") for (int k = 0; k < 2; ++k) dst[m][k] = *(const PG8_LAS bf16x8*)(lds + PG8_SA(b, h) + aoff + m * 2048 + k * 1024); } while (0)
; #define PG8_MMA(ai, bj, At, Bt) do { __builtin_amdgcn_s_setprio(1); _Pragma("unroll") for (int m = 0; m < 4; ++m) _Pragma("unroll") for (int n = 0; n < 2; ++n) _Pragma("unroll") for (int k = 0; k < 2; ++k) \
;         acc[ai][bj][m][n] = __builtin_amdgcn_mfma_f32_16x16x32_bf16(Bt[n][k], At[m][k], acc[ai][bj][m][n], 0, 0, 0); __builtin_amdgcn_s_setprio(0); } while (0)
; #define PG8_WAIT_V(n) asm volatile("s_waitcnt vmcnt(" #n ")" ::: "memory")
; #define PG8_WAIT_L(n) asm volatile("s_waitcnt lgkmcnt(" #n ")" ::: "memory")
; #define PG8_BAR __builtin_amdgcn_s_barrier()
; #define PG8_SCHED __builtin_amdgcn_sched_barrier(0)
; template <class Epi, class Sched, bool ALIGN_EPI = false, bool SP2 = false>
; __device__ __forceinline__ void gemm_phase(PG8_LAS unsigned char* lds, const Gemm g, const Sched& S, const Epi& E) {
;     ...
;             PG8_WAIT_V(8); PG8_WAIT_L(0); PG8_BAR; PG8_MMA(0, 0, At, B0); PG8_MMA(0, 1, At, B1); PG8_BAR; PG8_SCHED;
;             PG8_LDA(At, 0, 1); PG8_STAGE(PG8_SB(0, 0), b2, voffB); PG8_STAGE(PG8_SB(0, 1), b2 + hstep, voffB); PG8_STAGE(PG8_SA(0, 0), a2, voffA);
;             PG8_WAIT_V(8); PG8_WAIT_L(0); PG8_BAR; PG8_MMA(1, 0, At, B0); PG8_MMA(1, 1, At, B1); PG8_BAR; PG8_SCHED;
	v_mfma_f32_16x16x32_bf16 v[124:127], v[138:141], v[188:191], v[124:127]
	v_mfma_f32_16x16x32_bf16 v[120:123], v[164:167], v[188:191], v[120:123]
	v_mfma_f32_16x16x32_bf16 v[108:111], v[138:141], v[196:199], v[108:111]
	v_mfma_f32_16x16x32_bf16 v[104:107], v[164:167], v[196:199], v[104:107]
	v_mfma_f32_16x16x32_bf16 v[92:95], v[138:141], v[204:207], v[92:95]
	v_mfma_f32_16x16x32_bf16 v[88:91], v[164:167], v[204:207], v[88:91]
	v_mfma_f32_16x16x32_bf16 v[76:79], v[138:141], v[212:215], v[76:79]
	v_mfma_f32_16x16x32_bf16 v[72:75], v[164:167], v[212:215], v[72:75]
	v_mfma_f32_16x16x32_bf16 v[124:127], v[142:145], v[192:195], v[124:127]
	v_mfma_f32_16x16x32_bf16 v[120:123], v[168:171], v[192:195], v[120:123]
	v_mfma_f32_16x16x32_bf16 v[108:111], v[142:145], v[200:203], v[108:111]
	v_mfma_f32_16x16x32_bf16 v[104:107], v[168:171], v[200:203], v[104:107]
	v_mfma_f32_16x16x32_bf16 v[92:95], v[142:145], v[208:211], v[92:95]
	v_mfma_f32_16x16x32_bf16 v[88:91], v[168:171], v[208:211], v[88:91]
	v_mfma_f32_16x16x32_bf16 v[76:79], v[142:145], v[216:219], v[76:79]
	v_mfma_f32_16x16x32_bf16 v[72:75], v[168:171], v[216:219], v[72:75]
	s_setprio 0
	s_setprio 1
	v_mfma_f32_16x16x32_bf16 v[116:119], v[172:175], v[188:191], v[116:119]
	v_mfma_f32_16x16x32_bf16 v[112:115], v[180:183], v[188:191], v[112:115]
	v_mfma_f32_16x16x32_bf16 v[100:103], v[172:175], v[196:199], v[100:103]
	v_mfma_f32_16x16x32_bf16 v[96:99], v[180:183], v[196:199], v[96:99]
	v_mfma_f32_16x16x32_bf16 v[84:87], v[172:175], v[204:207], v[84:87]
	v_mfma_f32_16x16x32_bf16 v[80:83], v[180:183], v[204:207], v[80:83]
	v_mfma_f32_16x16x32_bf16 v[68:71], v[172:175], v[212:215], v[68:71]
	v_mfma_f32_16x16x32_bf16 v[64:67], v[180:183], v[212:215], v[64:67]
	v_mfma_f32_16x16x32_bf16 v[116:119], v[176:179], v[192:195], v[116:119]
	v_mfma_f32_16x16x32_bf16 v[112:115], v[184:187], v[192:195], v[112:115]
	v_mfma_f32_16x16x32_bf16 v[100:103], v[176:179], v[200:203], v[100:103]
	v_mfma_f32_16x16x32_bf16 v[96:99], v[184:187], v[200:203], v[96:99]
	v_mfma_f32_16x16x32_bf16 v[84:87], v[176:179], v[208:211], v[84:87]
	v_mfma_f32_16x16x32_bf16 v[80:83], v[184:187], v[208:211], v[80:83]
	v_mfma_f32_16x16x32_bf16 v[68:71], v[176:179], v[216:219], v[68:71]
	v_mfma_f32_16x16x32_bf16 v[64:67], v[184:187], v[216:219], v[64:67]
	s_setprio 0
	s_barrier
	s_add_i32 s51, s51, s30
	v_lshl_add_u64 v[146:147], s[4:5], 0, v[152:153]
	s_mov_b32 m0, s51
	ds_read_b128 v[188:191], v151 offset:16384
	ds_read_b128 v[192:195], v151 offset:17408
	ds_read_b128 v[196:199], v151 offset:18432
	ds_read_b128 v[200:203], v151 offset:19456
	ds_read_b128 v[204:207], v151 offset:20480
	ds_read_b128 v[208:211], v151 offset:21504
	ds_read_b128 v[212:215], v151 offset:22528
	ds_read_b128 v[216:219], v151 offset:23552
	global_load_lds_dwordx4 v[146:147], off
	s_add_i32 m0, s51, 0x2000
	s_add_u32 s52, s4, 0x80000
	v_lshl_add_u64 v[220:221], s[4:5], 0, v[128:129]
	s_addc_u32 s53, s5, 0
	s_add_i32 s51, s54, s30
	global_load_lds_dwordx4 v[220:221], off
	v_lshl_add_u64 v[222:223], s[52:53], 0, v[152:153]
	s_mov_b32 m0, s51
	v_lshl_add_u64 v[224:225], s[28:29], 0, v[130:131]
	global_load_lds_dwordx4 v[222:223], off
	v_lshl_add_u64 v[222:223], s[52:53], 0, v[128:129]
	s_add_i32 m0, s51, 0x2000
	s_nop 0
	global_load_lds_dwordx4 v[222:223], off
	v_lshl_add_u64 v[222:223], s[28:29], 0, v[132:133]
	s_mov_b32 m0, s35
	s_nop 0
	global_load_lds_dwordx4 v[222:223], off
	s_mov_b32 m0, s36
	s_nop 0
	global_load_lds_dwordx4 v[224:225], off
	s_waitcnt vmcnt(8)
	s_waitcnt lgkmcnt(0)
	s_setprio 1
	s_barrier
	v_mfma_f32_16x16x32_bf16 v[60:63], v[138:141], v[188:191], v[60:63]
	v_mfma_f32_16x16x32_bf16 v[56:59], v[164:167], v[188:191], v[56:59]
	v_mfma_f32_16x16x32_bf16 v[44:47], v[138:141], v[196:199], v[44:47]
	v_mfma_f32_16x16x32_bf16 v[40:43], v[164:167], v[196:199], v[40:43]
	v_mfma_f32_16x16x32_bf16 v[28:31], v[138:141], v[204:207], v[28:31]
	v_mfma_f32_16x16x32_bf16 v[24:27], v[164:167], v[204:207], v[24:27]
	v_mfma_f32_16x16x32_bf16 v[12:15], v[138:141], v[212:215], v[12:15]
	v_mfma_f32_16x16x32_bf16 v[8:11], v[164:167], v[212:215], v[8:11]
	v_mfma_f32_16x16x32_bf16 v[60:63], v[142:145], v[192:195], v[60:63]
	v_mfma_f32_16x16x32_bf16 v[56:59], v[168:171], v[192:195], v[56:59]
	v_mfma_f32_16x16x32_bf16 v[44:47], v[142:145], v[200:203], v[44:47]
	v_mfma_f32_16x16x32_bf16 v[40:43], v[168:171], v[200:203], v[40:43]
	v_mfma_f32_16x16x32_bf16 v[28:31], v[142:145], v[208:211], v[28:31]
	v_mfma_f32_16x16x32_bf16 v[24:27], v[168:171], v[208:211], v[24:27]
	v_mfma_f32_16x16x32_bf16 v[12:15], v[142:145], v[216:219], v[12:15]
	v_mfma_f32_16x16x32_bf16 v[8:11], v[168:171], v[216:219], v[8:11]
	s_setprio 0
	s_setprio 1
	v_mfma_f32_16x16x32_bf16 v[52:55], v[172:175], v[188:191], v[52:55]
	v_mfma_f32_16x16x32_bf16 v[48:51], v[180:183], v[188:191], v[48:51]
	v_mfma_f32_16x16x32_bf16 v[36:39], v[172:175], v[196:199], v[36:39]
	v_mfma_f32_16x16x32_bf16 v[32:35], v[180:183], v[196:199], v[32:35]
	v_mfma_f32_16x16x32_bf16 v[20:23], v[172:175], v[204:207], v[20:23]
	v_mfma_f32_16x16x32_bf16 v[16:19], v[180:183], v[204:207], v[16:19]
	v_mfma_f32_16x16x32_bf16 v[4:7], v[172:175], v[212:215], v[4:7]
	v_mfma_f32_16x16x32_bf16 v[0:3], v[180:183], v[212:215], v[0:3]
	v_mfma_f32_16x16x32_bf16 v[52:55], v[176:179], v[192:195], v[52:55]
	v_mfma_f32_16x16x32_bf16 v[48:51], v[184:187], v[192:195], v[48:51]
	v_mfma_f32_16x16x32_bf16 v[36:39], v[176:179], v[200:203], v[36:39]
	v_mfma_f32_16x16x32_bf16 v[32:35], v[184:187], v[200:203], v[32:35]
	v_mfma_f32_16x16x32_bf16 v[20:23], v[176:179], v[208:211], v[20:23]
	v_mfma_f32_16x16x32_bf16 v[16:19], v[184:187], v[208:211], v[16:19]
	v_mfma_f32_16x16x32_bf16 v[4:7], v[176:179], v[216:219], v[4:7]
	v_mfma_f32_16x16x32_bf16 v[0:3], v[184:187], v[216:219], v[0:3]
	s_setprio 0
	s_barrier
; #define PG8_STAGE(bufoff, gbase, voff) do { _Pragma("unroll") for (int _i = 0; _i < 2; ++_i) \
;         __builtin_amdgcn_global_load_lds((const unsigned*)((const char*)(gbase) + (voff)[_i]), (PG8_LAS unsigned*)(lds + (bufoff) + ldsw + _i * 8192), 16, 0, 0); } while (0)
; #define PG8_LDA(dst, b, h) do { _Pragma("unroll") for (int m = 0; m < 4; ++m) _Pragma("unroll") for (int k = 0; k < 2; ++k) dst[m][k] = *(const PG8_LAS bf16x8*)(lds + PG8_SA(b, h) + aoff + m * 2048 + k * 1024); } while (0)
; #define PG8_LDB(dst, b, h) do { _Pragma("unroll") for (int n = 0; n < 2; ++n) _Pragma("unroll") for (int k = 0; k < 2; ++k) dst[n][k] = *(const PG8_LAS bf16x8*)(lds + PG8_SB(b, h) + boff + n * 2048 + k * 1024); } while (0)
; #define PG8_MMA(ai, bj, At, Bt) do { __builtin_amdgcn_s_setprio(1); _Pragma("unroll") for (int m = 0; m < 4; ++m) _Pragma("unroll") for (int n = 0; n < 2; ++n) _Pragma("unroll") for (int k = 0; k < 2; ++k) \
;         acc[ai][bj][m][n] = __builtin_amdgcn_mfma_f32_16x16x32_bf16(Bt[n][k], At[m][k], acc[ai][bj][m][n], 0, 0, 0); __builtin_amdgcn_s_setprio(0); } while (0)
; #define PG8_WAIT_V(n) asm volatile("s_waitcnt vmcnt(" #n ")" ::: "memory")
; #define PG8_WAIT_L(n) asm volatile("s_waitcnt lgkmcnt(" #n ")" ::: "memory")
; #define PG8_BAR __builtin_amdgcn_s_barrier()
; #define PG8_SCHED __builtin_amdgcn_sched_barrier(0)
; template <class Epi, class Sched, bool ALIGN_EPI = false, bool SP2 = false>
; __device__ __forceinline__ void gemm_phase(PG8_LAS unsigned char* lds, const Gemm g, const Sched& S, const Epi& E) {
;     ...
;             PG8_LDB(B0, 1, 0); PG8_LDB(B1, 1, 1); PG8_SCHED; PG8_LDA(At, 1, 0); PG8_STAGE(PG8_SA(0, 1), a2 + hstep, voffA);
;             PG8_WAIT_V(8); PG8_WAIT_L(0); PG8_BAR; PG8_MMA(0, 0, At, B0); PG8_MMA(0, 1, At, B1); PG8_BAR; PG8_SCHED;
	s_add_i32 s51, 0, 0x18000
	s_add_i32 s52, 0, 0x1c000
	v_add_u32_e32 v168, s51, v150
	v_add_u32_e32 v184, s52, v150
	ds_read_b128 v[138:141], v168
	ds_read_b128 v[142:145], v168 offset:1024
	ds_read_b128 v[164:167], v168 offset:2048
	ds_read_b128 v[168:171], v168 offset:3072
	ds_read_b128 v[172:175], v184
	ds_read_b128 v[176:179], v184 offset:1024
	ds_read_b128 v[180:183], v184 offset:2048
	ds_read_b128 v[184:187], v184 offset:3072
	s_add_u32 s28, s28, 0x80000
	s_addc_u32 s29, s29, 0
	s_mov_b32 m0, s37
	v_lshl_add_u64 v[226:227], s[28:29], 0, v[132:133]
	ds_read_b128 v[188:191], v151 offset:32768
	ds_read_b128 v[192:195], v151 offset:33792
	ds_read_b128 v[196:199], v151 offset:34816
	ds_read_b128 v[200:203], v151 offset:35840
	ds_read_b128 v[204:207], v151 offset:36864
	ds_read_b128 v[208:211], v151 offset:37888
	ds_read_b128 v[212:215], v151 offset:38912
	ds_read_b128 v[216:219], v151 offset:39936
	global_load_lds_dwordx4 v[226:227], off
	v_lshl_add_u64 v[226:227], s[28:29], 0, v[130:131]
	s_mov_b32 m0, s38
	s_nop 0
	global_load_lds_dwordx4 v[226:227], off
	s_waitcnt vmcnt(8)
	s_waitcnt lgkmcnt(0)
	s_setprio 1
	s_barrier
	v_mfma_f32_16x16x32_bf16 v[124:127], v[138:141], v[188:191], v[124:127]
	v_mfma_f32_16x16x32_bf16 v[120:123], v[164:167], v[188:191], v[120:123]
	v_mfma_f32_16x16x32_bf16 v[108:111], v[138:141], v[196:199], v[108:111]
	v_mfma_f32_16x16x32_bf16 v[104:107], v[164:167], v[196:199], v[104:107]
	v_mfma_f32_16x16x32_bf16 v[92:95], v[138:141], v[204:207], v[92:95]
	v_mfma_f32_16x16x32_bf16 v[88:91], v[164:167], v[204:207], v[88:91]
	v_mfma_f32_16x16x32_bf16 v[76:79], v[138:141], v[212:215], v[76:79]
	v_mfma_f32_16x16x32_bf16 v[72:75], v[164:167], v[212:215], v[72:75]
	v_mfma_f32_16x16x32_bf16 v[124:127], v[142:145], v[192:195], v[124:127]
	v_mfma_f32_16x16x32_bf16 v[120:123], v[168:171], v[192:195], v[120:123]
	v_mfma_f32_16x16x32_bf16 v[108:111], v[142:145], v[200:203], v[108:111]
	v_mfma_f32_16x16x32_bf16 v[104:107], v[168:171], v[200:203], v[104:107]
	v_mfma_f32_16x16x32_bf16 v[92:95], v[142:145], v[208:211], v[92:95]
	v_mfma_f32_16x16x32_bf16 v[88:91], v[168:171], v[208:211], v[88:91]
	v_mfma_f32_16x16x32_bf16 v[76:79], v[142:145], v[216:219], v[76:79]
	v_mfma_f32_16x16x32_bf16 v[72:75], v[168:171], v[216:219], v[72:75]
	s_setprio 0
	s_setprio 1
	v_mfma_f32_16x16x32_bf16 v[116:119], v[172:175], v[188:191], v[116:119]
	v_mfma_f32_16x16x32_bf16 v[112:115], v[180:183], v[188:191], v[112:115]
	v_mfma_f32_16x16x32_bf16 v[100:103], v[172:175], v[196:199], v[100:103]
	v_mfma_f32_16x16x32_bf16 v[96:99], v[180:183], v[196:199], v[96:99]
	v_mfma_f32_16x16x32_bf16 v[84:87], v[172:175], v[204:207], v[84:87]
	v_mfma_f32_16x16x32_bf16 v[80:83], v[180:183], v[204:207], v[80:83]
	v_mfma_f32_16x16x32_bf16 v[68:71], v[172:175], v[212:215], v[68:71]
	v_mfma_f32_16x16x32_bf16 v[64:67], v[180:183], v[212:215], v[64:67]
	v_mfma_f32_16x16x32_bf16 v[116:119], v[176:179], v[192:195], v[116:119]
	v_mfma_f32_16x16x32_bf16 v[112:115], v[184:187], v[192:195], v[112:115]
	v_mfma_f32_16x16x32_bf16 v[100:103], v[176:179], v[200:203], v[100:103]
	v_mfma_f32_16x16x32_bf16 v[96:99], v[184:187], v[200:203], v[96:99]
	v_mfma_f32_16x16x32_bf16 v[84:87], v[176:179], v[208:211], v[84:87]
	v_mfma_f32_16x16x32_bf16 v[80:83], v[184:187], v[208:211], v[80:83]
	v_mfma_f32_16x16x32_bf16 v[68:71], v[176:179], v[216:219], v[68:71]
	v_mfma_f32_16x16x32_bf16 v[64:67], v[184:187], v[216:219], v[64:67]
	s_setprio 0
	s_barrier
; #define PG8_STAGE(bufoff, gbase, voff) do { _Pragma("unroll") for (int _i = 0; _i < 2; ++_i) \
;         __builtin_amdgcn_global_load_lds((const unsigned*)((const char*)(gbase) + (voff)[_i]), (PG8_LAS unsigned*)(lds + (bufoff) + ldsw + _i * 8192), 16, 0, 0); } while (0)
; #define PG8_LDA(dst, b, h) do { _Pragma("unroll") for (int m = 0; m < 4; ++m) _Pragma("unroll") for (int k = 0; k < 2; ++k) dst[m][k] = *(const PG8_LAS bf16x8*)(lds + PG8_SA(b, h) + aoff + m * 2048 + k * 1024); } while (0)
; #define PG8_MMA(ai, bj, At, Bt) do { __builtin_amdgcn_s_setprio(1); _Pragma("unroll") for (int m = 0; m < 4; ++m) _Pragma("unroll") for (int n = 0; n < 2; ++n) _Pragma("unroll") for (int k = 0; k < 2; ++k) \
;         acc[ai][bj][m][n] = __builtin_amdgcn_mfma_f32_16x16x32_bf16(Bt[n][k], At[m][k], acc[ai][bj][m][n], 0, 0, 0); __builtin_amdgcn_s_setprio(0); } while (0)
; #define PG8_WAIT_V(n) asm volatile("s_waitcnt vmcnt(" #n ")" ::: "memory")
; #define PG8_WAIT_L(n) asm volatile("s_waitcnt lgkmcnt(" #n ")" ::: "memory")
; #define PG8_BAR __builtin_amdgcn_s_barrier()
; #define PG8_SCHED __builtin_amdgcn_sched_barrier(0)
; template <class Epi, class Sched, bool ALIGN_EPI = false, bool SP2 = false>
; __device__ __forceinline__ void gemm_phase(PG8_LAS unsigned char* lds, const Gemm g, const Sched& S, const Epi& E) {
;     ...
;             PG8_LDA(At, 1, 1); PG8_STAGE(PG8_SB(1, 0), b3, voffB); PG8_STAGE(PG8_SB(1, 1), b3 + hstep, voffB); PG8_STAGE(PG8_SA(1, 0), a3, voffA);
;             PG8_WAIT_V(8); PG8_WAIT_L(0); PG8_BAR; PG8_MMA(1, 0, At, B0); PG8_MMA(1, 1, At, B1); PG8_BAR; PG8_SCHED;
	s_add_i32 s28, s51, s30
	v_lshl_add_u64 v[146:147], v[146:147], 0, s[74:75]
	s_mov_b32 m0, s28
	ds_read_b128 v[188:191], v151 offset:49152
	ds_read_b128 v[192:195], v151 offset:50176
	ds_read_b128 v[196:199], v151 offset:51200
	ds_read_b128 v[200:203], v151 offset:52224
	ds_read_b128 v[204:207], v151 offset:53248
	ds_read_b128 v[208:211], v151 offset:54272
	ds_read_b128 v[212:215], v151 offset:55296
	ds_read_b128 v[216:219], v151 offset:56320
	global_load_lds_dwordx4 v[146:147], off
	s_add_i32 m0, s28, 0x2000
	s_add_u32 s4, s4, 0x80080
	v_lshl_add_u64 v[146:147], v[220:221], 0, s[74:75]
	s_addc_u32 s5, s5, 0
	s_add_i32 s28, s52, s30
	global_load_lds_dwordx4 v[146:147], off
	v_lshl_add_u64 v[146:147], s[4:5], 0, v[152:153]
	s_mov_b32 m0, s28
	s_nop 0
	global_load_lds_dwordx4 v[146:147], off
	v_lshl_add_u64 v[146:147], s[4:5], 0, v[128:129]
	s_add_i32 m0, s28, 0x2000
	s_nop 0
	global_load_lds_dwordx4 v[146:147], off
	v_lshl_add_u64 v[146:147], v[222:223], 0, s[74:75]
	s_mov_b32 m0, s42
	s_nop 0
	global_load_lds_dwordx4 v[146:147], off
	v_lshl_add_u64 v[146:147], v[224:225], 0, s[74:75]
	s_mov_b32 m0, s43
	s_nop 0
	global_load_lds_dwordx4 v[146:147], off
	s_waitcnt vmcnt(8)
	s_waitcnt lgkmcnt(0)
	s_setprio 1
	s_barrier
	v_mfma_f32_16x16x32_bf16 v[60:63], v[138:141], v[188:191], v[60:63]
	v_mfma_f32_16x16x32_bf16 v[56:59], v[164:167], v[188:191], v[56:59]
	v_mfma_f32_16x16x32_bf16 v[44:47], v[138:141], v[196:199], v[44:47]
	v_mfma_f32_16x16x32_bf16 v[40:43], v[164:167], v[196:199], v[40:43]
	v_mfma_f32_16x16x32_bf16 v[28:31], v[138:141], v[204:207], v[28:31]
	v_mfma_f32_16x16x32_bf16 v[24:27], v[164:167], v[204:207], v[24:27]
	v_mfma_f32_16x16x32_bf16 v[12:15], v[138:141], v[212:215], v[12:15]
	v_mfma_f32_16x16x32_bf16 v[8:11], v[164:167], v[212:215], v[8:11]
	v_mfma_f32_16x16x32_bf16 v[60:63], v[142:145], v[192:195], v[60:63]
	v_mfma_f32_16x16x32_bf16 v[56:59], v[168:171], v[192:195], v[56:59]
	v_mfma_f32_16x16x32_bf16 v[44:47], v[142:145], v[200:203], v[44:47]
	v_mfma_f32_16x16x32_bf16 v[40:43], v[168:171], v[200:203], v[40:43]
	v_mfma_f32_16x16x32_bf16 v[28:31], v[142:145], v[208:211], v[28:31]
	v_mfma_f32_16x16x32_bf16 v[24:27], v[168:171], v[208:211], v[24:27]
	v_mfma_f32_16x16x32_bf16 v[12:15], v[142:145], v[216:219], v[12:15]
	v_mfma_f32_16x16x32_bf16 v[8:11], v[168:171], v[216:219], v[8:11]
	s_setprio 0
	s_setprio 1
	v_mfma_f32_16x16x32_bf16 v[52:55], v[172:175], v[188:191], v[52:55]
	v_mfma_f32_16x16x32_bf16 v[48:51], v[180:183], v[188:191], v[48:51]
	v_mfma_f32_16x16x32_bf16 v[36:39], v[172:175], v[196:199], v[36:39]
	v_mfma_f32_16x16x32_bf16 v[32:35], v[180:183], v[196:199], v[32:35]
	v_mfma_f32_16x16x32_bf16 v[20:23], v[172:175], v[204:207], v[20:23]
	v_mfma_f32_16x16x32_bf16 v[16:19], v[180:183], v[204:207], v[16:19]
	v_mfma_f32_16x16x32_bf16 v[4:7], v[172:175], v[212:215], v[4:7]
	v_mfma_f32_16x16x32_bf16 v[0:3], v[180:183], v[212:215], v[0:3]
	v_mfma_f32_16x16x32_bf16 v[52:55], v[176:179], v[192:195], v[52:55]
	v_mfma_f32_16x16x32_bf16 v[48:51], v[184:187], v[192:195], v[48:51]
	v_mfma_f32_16x16x32_bf16 v[36:39], v[176:179], v[200:203], v[36:39]
	v_mfma_f32_16x16x32_bf16 v[32:35], v[184:187], v[200:203], v[32:35]
	v_mfma_f32_16x16x32_bf16 v[20:23], v[176:179], v[208:211], v[20:23]
	v_mfma_f32_16x16x32_bf16 v[16:19], v[184:187], v[208:211], v[16:19]
	v_mfma_f32_16x16x32_bf16 v[4:7], v[176:179], v[216:219], v[4:7]
	v_mfma_f32_16x16x32_bf16 v[0:3], v[184:187], v[216:219], v[0:3]
	s_setprio 0
	s_barrier
	s_add_i32 s50, s50, 2
	s_add_u32 s0, s0, 0x100
	s_addc_u32 s1, s1, 0
	s_add_u32 s48, s48, 0x100
	s_addc_u32 s49, s49, 0
	s_cmp_gt_u32 s50, 29
	s_cbranch_scc0 .LBB0_221
	s_and_b64 vcc, exec, s[20:21]
	s_cbranch_vccz .LBB0_224
	s_barrier

; __device__ __forceinline__ unsigned xb_ld(unsigned* p)              { return __hip_atomic_load(p, __ATOMIC_RELAXED, __HIP_MEMORY_SCOPE_AGENT); }
; __device__ __forceinline__ unsigned xb_add(unsigned* p, unsigned v) { return __hip_atomic_fetch_add(p, v, __ATOMIC_RELAXED, __HIP_MEMORY_SCOPE_AGENT); }
; #define XB_SPIN(cond, bar) do { unsigned _sp = 0; while (cond) { __builtin_amdgcn_s_sleep(1); \
;     if ((++_sp & 255u) == 0u) { if (xb_ld(&(bar)[XB_TMO])) break; if (_sp > XB_SPIN_CAP) { atomicAdd(&(bar)[XB_TMO], 1u); break; } } } } while (0)
; __device__ __forceinline__ void xcd_barrier(const XcdBarrier& b) {
;     ...
;             const unsigned og = xb_add(&bar[XB_TOP], 1u);
;             const unsigned tg = og / nx;
;             if (og + 1u == (tg + 1u) * nx) xb_add(&bar[XB_TOPGEN], 1u);
;             else XB_SPIN(xb_ld(&bar[XB_TOPGEN]) == tg, bar);
;             __builtin_amdgcn_fence(__ATOMIC_ACQUIRE, "agent");
.LBB0_312:
	s_or_b64 exec, exec, s[8:9]
	buffer_inv sc1
	s_waitcnt vmcnt(1)
	v_readfirstlane_b32 s6, v2
	v_cvt_f32_u32_e32 v2, v0
	v_sub_u32_e32 v3, 0, v0
	v_add_u32_e32 v1, s6, v1
	s_add_u32 s6, s2, 0x2e403500
	v_rcp_iflag_f32_e32 v2, v2
	s_addc_u32 s7, s3, 0
	s_mov_b64 s[10:11], -1
	v_mul_f32_e32 v2, 0x4f7ffffe, v2
	v_cvt_u32_f32_e32 v2, v2
	v_mul_lo_u32 v3, v3, v2
	v_mul_hi_u32 v3, v2, v3
	v_add_u32_e32 v2, v2, v3
	v_mul_hi_u32 v2, v1, v2
	v_mul_lo_u32 v3, v2, v0
	v_sub_u32_e32 v3, v1, v3
	v_cmp_ge_u32_e32 vcc, v3, v0
	v_add_u32_e32 v4, 1, v2
	v_add_u32_e32 v1, 1, v1
	v_cndmask_b32_e32 v2, v2, v4, vcc
	v_sub_u32_e32 v4, v3, v0
	v_cndmask_b32_e32 v3, v3, v4, vcc
	v_cmp_ge_u32_e32 vcc, v3, v0
	v_add_u32_e32 v3, 1, v2
	s_nop 0
	v_cndmask_b32_e32 v2, v2, v3, vcc
	v_mul_lo_u32 v3, v0, v2
	v_add_u32_e32 v0, v3, v0
	v_cmp_ne_u32_e32 vcc, v1, v0
	v_mov_b32_e32 v2, v0
	v_mov_b64_e32 v[0:1], s[6:7]
	s_and_saveexec_b64 s[8:9], vcc
	s_cbranch_execz .LBB0_324
	global_load_dword v0, v153, s[6:7] offset:-256 sc1
	s_mov_b64 s[14:15], 0
	s_waitcnt vmcnt(0)
	v_cmp_lt_u32_e32 vcc, v0, v2
	s_and_saveexec_b64 s[12:13], vcc
	s_cbranch_execz .LBB0_323
	s_add_u32 s10, s2, 0x2e400200
	s_addc_u32 s11, s3, 0
	s_mov_b32 s22, 1
	s_mov_b64 s[2:3], 0
	s_branch .LBB0_316

; __device__ __forceinline__ unsigned xb_ld(unsigned* p)              { return __hip_atomic_load(p, __ATOMIC_RELAXED, __HIP_MEMORY_SCOPE_AGENT); }
; #define XB_SPIN(cond, bar) do { unsigned _sp = 0; while (cond) { __builtin_amdgcn_s_sleep(1); \
;     if ((++_sp & 255u) == 0u) { if (xb_ld(&(bar)[XB_TMO])) break; if (_sp > XB_SPIN_CAP) { atomicAdd(&(bar)[XB_TMO], 1u); break; } } } } while (0)
; __device__ __forceinline__ void xcd_barrier(const XcdBarrier& b) {
;     ...
;             else XB_SPIN(xb_ld(&bar[XB_TOPGEN]) == tg, bar);
.LBB0_318:
	global_load_dword v0, v153, s[6:7] offset:-256 sc1
	s_add_i32 s22, s22, 1
	s_mov_b64 s[18:19], -1
	s_waitcnt vmcnt(0)
	v_cmp_ge_u32_e32 vcc, v0, v2
	s_orn2_b64 s[16:17], vcc, exec
	s_branch .LBB0_315

; __device__ __forceinline__ unsigned xb_add(unsigned* p, unsigned v) { return __hip_atomic_fetch_add(p, v, __ATOMIC_RELAXED, __HIP_MEMORY_SCOPE_AGENT); }
; __device__ __forceinline__ void xcd_barrier(const XcdBarrier& b) {
;     ...
;             __builtin_amdgcn_fence(__ATOMIC_ACQUIRE, "agent");
;             xb_add(&bar[XB_XGEN(b.x)], 1u);
;             asm volatile("s_waitcnt vmcnt(0)" ::: "memory");
.LBB0_326:
	s_or_b64 exec, exec, s[2:3]
	s_mov_b64 s[2:3], exec
	v_mbcnt_lo_u32_b32 v0, s2, 0
	v_mbcnt_hi_u32_b32 v0, s3, v0
	v_cmp_eq_u32_e32 vcc, 0, v0
	s_waitcnt vmcnt(0)
	s_and_saveexec_b64 s[6:7], vcc
	s_cbranch_execz .LBB0_328
	s_bcnt1_i32_b64 s2, s[2:3]
	v_mov_b32_e32 v0, s2
	v_mov_b32_e32 v1, 0x2000
	global_atomic_add v1, v0, s[4:5] offset:1024

; #define PG8_STAGE(bufoff, gbase, voff) do { _Pragma("unroll") for (int _i = 0; _i < 2; ++_i) \
;         __builtin_amdgcn_global_load_lds((const unsigned*)((const char*)(gbase) + (voff)[_i]), (PG8_LAS unsigned*)(lds + (bufoff) + ldsw + _i * 8192), 16, 0, 0); } while (0)
; #define PG8_WAIT_V(n) asm volatile("s_waitcnt vmcnt(" #n ")" ::: "memory")
; #define PG8_BAR __builtin_amdgcn_s_barrier()
; template <class Epi, class Sched, bool ALIGN_EPI = false, bool SP2 = false>
; __device__ __forceinline__ void gemm_phase(PG8_LAS unsigned char* lds, const Gemm g, const Sched& S, const Epi& E) {
;     ...
;     const int aoff = lds_byte(wr * 64 + fr, fq * 8), boff = lds_byte(wc * 32 + fr, fq * 8);
;     ...
;         PG8_STAGE(PG8_SB(0, 0), cB, voffB); PG8_STAGE(PG8_SB(0, 1), cB + hstep, voffB); PG8_STAGE(PG8_SA(0, 0), cA, voffA); PG8_STAGE(PG8_SA(0, 1), cA + hstep, voffA);
;         if (wr == 1) PG8_BAR;
;         PG8_WAIT_V(2); PG8_BAR;
;         PG8_STAGE(PG8_SB(1, 0), cB + kstep, voffB); PG8_STAGE(PG8_SA(1, 0), cA + kstep, voffA); PG8_STAGE(PG8_SB(1, 1), cB + hstep + kstep, voffB);
;         PG8_WAIT_V(6); PG8_BAR;
.LBB0_437:
	s_add_u32 s18, s14, 0x1a600000
	s_addc_u32 s19, s15, 0
	s_add_u32 s20, s14, 0x1ba00000
	s_addc_u32 s21, s15, 0
	s_add_u32 s22, s14, 0x1be00000
	s_addc_u32 s23, s15, 0
	s_add_u32 s24, s14, 0x1ce00000
	s_addc_u32 s25, s15, 0
	s_add_u32 s26, s14, 0x2e200000
	s_addc_u32 s27, s15, 0
	s_add_u32 s28, s14, 0x2e500000
	s_addc_u32 s29, s15, 0
	s_add_u32 s30, s14, 0x2e300000
	s_addc_u32 s31, s15, 0
	s_add_u32 s34, s14, 0x2e340000
	s_addc_u32 s35, s15, 0
	s_lshl_b64 s[36:37], s[72:73], 19
	s_add_u32 s3, s12, s36
	s_addc_u32 s33, s13, s37
	s_add_u32 s36, s3, 0x4140000
	s_addc_u32 s37, s33, 0
	s_lshl_b64 s[38:39], s[72:73], 15
	s_add_u32 s9, s12, s38
	s_addc_u32 s39, s13, s39
	s_add_u32 s38, s9, 0x4240000
	s_addc_u32 s39, s39, 0
	s_and_b32 s7, s7, 3
	s_add_i32 m0, s55, 0x18000
	v_lshl_add_u64 v[6:7], v[6:7], 0, s[74:75]
	s_mov_b64 s[86:87], s[72:73]
	s_lshl_b32 s70, s8, 6
	s_lshl_b32 s40, s8, 13
	s_lshl_b32 s71, s7, 5
	s_lshl_b32 s41, s7, 12
	s_waitcnt vmcnt(2)
	s_barrier
	global_load_lds_dwordx4 v[6:7], off
	v_lshl_add_u64 v[4:5], v[4:5], 0, s[74:75]
	s_add_i32 m0, s55, 0x1a000
	s_add_i32 s72, s55, 0x8000
	s_add_i32 s73, s55, 0xa000
	global_load_lds_dwordx4 v[4:5], off
	v_lshl_add_u64 v[0:1], v[0:1], 0, s[74:75]
	s_mov_b32 m0, s72
	s_add_u32 s8, s4, 0x80080
	global_load_lds_dwordx4 v[0:1], off
	v_lshl_add_u64 v[0:1], v[2:3], 0, s[74:75]
	s_mov_b32 m0, s73
	s_addc_u32 s9, s5, 0
	global_load_lds_dwordx4 v[0:1], off
	s_add_i32 m0, s55, 0x1c000
	v_lshl_add_u64 v[0:1], s[8:9], 0, v[166:167]
	global_load_lds_dwordx4 v[0:1], off
	v_lshl_add_u64 v[0:1], s[8:9], 0, v[170:171]
	s_add_i32 m0, s55, 0x1e000
	v_bfe_u32 v191, v8, 4, 2
	global_load_lds_dwordx4 v[0:1], off
	v_and_b32_e32 v190, 15, v8
	v_lshlrev_b32_e32 v0, 4, v191
	v_lshlrev_b32_e32 v1, 2, v8
	s_or_b32 s74, s71, 0xfffffb00
	v_lshl_or_b32 v0, v190, 6, v0
	v_and_b32_e32 v1, 32, v1
	s_cmpk_lt_u32 s6, 0x100
	v_bitop3_b32 v2, v0, s40, v1 bitop3:0xde
	v_bitop3_b32 v192, v0, s41, v1 bitop3:0xde
	s_cselect_b64 s[40:41], -1, 0
	s_and_b32 s77, s6, 0xc0
	s_or_b32 s75, s71, 0xfffffa00
	s_lshl_b32 s76, s7, 6
	s_or_b32 s78, s77, 0x400
	s_or_b32 s79, s77, 0x420
	s_lshl_b32 s6, s7, 7
	v_lshlrev_b32_e32 v0, 15, v9
	s_add_u32 s6, s14, s6
	v_and_b32_e32 v0, 0xffff0000, v0
	s_addc_u32 s8, s15, 0
	v_lshl_add_u32 v0, v10, 12, v0
	v_and_b32_e32 v1, 1, v9
	s_add_u32 s42, s6, 0x1b600000
	v_lshl_or_b32 v0, v1, 6, v0
	s_addc_u32 s43, s8, 0
	s_lshl_b32 s6, s7, 8
	v_lshl_add_u32 v172, v11, 1, v0
	v_lshlrev_b32_e32 v0, 15, v12
	s_add_u32 s3, s3, s6
	v_and_b32_e32 v0, 0xffff0000, v0
	s_waitcnt vmcnt(6)
	s_addc_u32 s6, s33, 0
	v_lshl_add_u32 v0, v13, 12, v0
	v_and_b32_e32 v1, 1, v12
	s_add_u32 s44, s3, 0x4040000
	v_lshl_or_b32 v0, v1, 6, v0
	s_addc_u32 s45, s6, 0
	v_mov_b32_e32 v173, v153
	v_lshl_add_u32 v174, v14, 1, v0
	v_mov_b32_e32 v175, v153
	s_mov_b32 s80, 0
	v_add_u32_e32 v193, 0, v2
	s_barrier
	s_branch .LBB0_440
	s_nop 0
	s_nop 0
	s_nop 0
	s_nop 0
	s_nop 0
	s_nop 0
	s_nop 0
	s_nop 0
	s_nop 0
	s_nop 0
	s_nop 0
	s_nop 0
	s_nop 0
	s_nop 0
	s_nop 0
	s_nop 0
	s_nop 0
	s_nop 0
	s_nop 0
	s_nop 0
	s_nop 0
	s_nop 0
	s_nop 0
	s_nop 0
	s_nop 0
	s_nop 0
	s_nop 0
	s_nop 0
	s_nop 0
	s_nop 0
	s_nop 0
	s_nop 0
	s_nop 0
	s_nop 0
	s_nop 0
	s_nop 0
	s_nop 0
	s_nop 0
	s_nop 0
	s_nop 0
	s_nop 0
	s_nop 0
	s_nop 0
	s_nop 0
	s_nop 0
	s_nop 0
	s_nop 0
	s_nop 0
	s_nop 0
	s_nop 0
	s_nop 0
	s_nop 0
	s_nop 0
	s_nop 0
	s_nop 0
	s_nop 0
	s_nop 0
	s_nop 0
	s_nop 0
	s_nop 0
	s_nop 0
	s_nop 0
	s_nop 0
	s_nop 0
	s_nop 0
	s_nop 0
	s_nop 0
	s_nop 0
	s_nop 0
	s_nop 0
	s_nop 0
	s_nop 0
	s_nop 0
	s_nop 0
	s_nop 0
	s_nop 0
	s_nop 0
	s_nop 0
	s_nop 0
	s_nop 0
	s_nop 0
	s_nop 0
	s_nop 0
	s_nop 0
	s_nop 0
	s_nop 0
	s_nop 0
	s_nop 0
	s_nop 0
	s_nop 0
	s_nop 0
	s_nop 0
	s_nop 0
	s_nop 0
	s_nop 0
	s_nop 0
	s_nop 0
	s_nop 0
	s_nop 0
	s_nop 0
	s_nop 0
	s_nop 0
	s_nop 0
	s_nop 0
	s_nop 0
	s_nop 0
	s_nop 0
	s_nop 0
	s_nop 0
	s_nop 0
	s_nop 0
	s_nop 0
	s_nop 0
	s_nop 0
	s_nop 0
	s_nop 0
	s_nop 0
	s_nop 0
	s_nop 0
	s_nop 0
	s_nop 0
	s_nop 0
	s_nop 0
	s_nop 0
	s_nop 0
	s_nop 0
	s_nop 0

; #define PG8_STAGE(bufoff, gbase, voff) do { _Pragma("unroll") for (int _i = 0; _i < 2; ++_i) \
;         __builtin_amdgcn_global_load_lds((const unsigned*)((const char*)(gbase) + (voff)[_i]), (PG8_LAS unsigned*)(lds + (bufoff) + ldsw + _i * 8192), 16, 0, 0); } while (0)
; #define PG8_WAIT_V(n) asm volatile("s_waitcnt vmcnt(" #n ")" ::: "memory")
; #define PG8_BAR __builtin_amdgcn_s_barrier()
; template <class Epi, class Sched, bool ALIGN_EPI = false, bool SP2 = false>
; __device__ __forceinline__ void gemm_phase(PG8_LAS unsigned char* lds, const Gemm g, const Sched& S, const Epi& E) {
;     ...
;     f32x4 acc[2][2][4][2];
; #pragma unroll
;     for (int a = 0; a < 2; ++a)
; #pragma unroll
;         for (int b = 0; b < 2; ++b)
; #pragma unroll
;             for (int m = 0; m < 4; ++m)
; #pragma unroll
;                 for (int n = 0; n < 2; ++n) acc[a][b][m][n] = (f32x4){0.f, 0.f, 0.f, 0.f};
;     ...
;         PG8_STAGE(PG8_SB(0, 0), cB, voffB); PG8_STAGE(PG8_SB(0, 1), cB + hstep, voffB); PG8_STAGE(PG8_SA(0, 0), cA, voffA); PG8_STAGE(PG8_SA(0, 1), cA + hstep, voffA);
;         if (wr == 1) PG8_BAR;
;         PG8_WAIT_V(2); PG8_BAR;
;         PG8_STAGE(PG8_SB(1, 0), cB + kstep, voffB); PG8_STAGE(PG8_SA(1, 0), cA + kstep, voffA); PG8_STAGE(PG8_SB(1, 1), cB + hstep + kstep, voffB);
;         PG8_WAIT_V(6); PG8_BAR;
.LBB0_873:
	v_lshl_add_u64 v[6:7], s[24:25], 0, v[152:153]
	v_mov_b32_e32 v33, v153
	v_lshl_add_u64 v[8:9], s[24:25], 0, v[32:33]
	v_mov_b32_e32 v41, v153
	s_and_b32 s34, s5, 3
	s_add_i32 m0, s35, 0x18000
	v_lshl_add_u64 v[6:7], v[6:7], 0, s[74:75]
	v_lshl_add_u64 v[10:11], s[14:15], 0, v[40:41]
	v_mov_b32_e32 v35, v153
	s_lshl_b32 s36, s4, 6
	s_lshl_b32 s4, s4, 13
	s_lshl_b32 s5, s34, 12
	s_waitcnt vmcnt(2)
	s_barrier
	global_load_lds_dwordx4 v[6:7], off
	v_lshl_add_u64 v[6:7], v[8:9], 0, s[74:75]
	s_add_i32 m0, s35, 0x1a000
	s_add_i32 s40, s35, 0x8000
	s_add_i32 s41, s35, 0xa000
	v_lshl_add_u64 v[12:13], s[14:15], 0, v[34:35]
	global_load_lds_dwordx4 v[6:7], off
	v_lshl_add_u64 v[6:7], v[10:11], 0, s[74:75]
	s_mov_b32 m0, s40
	s_add_u32 s0, s24, 0x80080
	global_load_lds_dwordx4 v[6:7], off
	v_lshl_add_u64 v[6:7], v[12:13], 0, s[74:75]
	s_mov_b32 m0, s41
	s_addc_u32 s1, s25, 0
	global_load_lds_dwordx4 v[6:7], off
	s_add_i32 m0, s35, 0x1c000
	v_lshl_add_u64 v[6:7], s[0:1], 0, v[152:153]
	global_load_lds_dwordx4 v[6:7], off
	v_lshl_add_u64 v[6:7], s[0:1], 0, v[32:33]
	s_add_i32 m0, s35, 0x1e000
	v_and_b32_e32 v144, 15, v220
	global_load_lds_dwordx4 v[6:7], off
	v_and_b32_e32 v6, 48, v220
	v_lshlrev_b32_e32 v7, 2, v220
	v_lshl_or_b32 v6, v144, 6, v6
	v_and_b32_e32 v7, 32, v7
	v_bitop3_b32 v8, v6, s4, v7 bitop3:0xde
	v_bitop3_b32 v50, v6, s5, v7 bitop3:0xde
	v_lshlrev_b32_e32 v6, 15, v4
	v_and_b32_e32 v6, 0xffff0000, v6
	v_lshl_add_u32 v3, v3, 12, v6
	v_and_b32_e32 v4, 1, v4
	v_lshl_or_b32 v3, v4, 6, v3
	v_lshl_add_u32 v42, v5, 1, v3
	v_lshlrev_b32_e32 v3, 15, v0
	v_and_b32_e32 v3, 0xffff0000, v3
	v_lshl_add_u32 v1, v1, 12, v3
	v_and_b32_e32 v0, 1, v0
	v_lshl_or_b32 v0, v0, 6, v1
	s_waitcnt vmcnt(6)
	v_lshl_add_u32 v44, v2, 1, v0
	v_mov_b32_e32 v2, v153
	v_mov_b32_e32 v3, v153
	v_readlane_b32 s0, v253, 27
	v_mov_b32_e32 v0, v153
	v_mov_b32_e32 v1, v153
	v_add_u32_e32 v51, 0, v8
	v_mov_b64_e32 v[6:7], v[2:3]
	v_mov_b64_e32 v[18:19], v[2:3]
	v_mov_b64_e32 v[22:23], v[2:3]
	v_mov_b64_e32 v[38:39], v[2:3]
	v_mov_b64_e32 v[54:55], v[2:3]
	v_mov_b64_e32 v[66:67], v[2:3]
	v_mov_b64_e32 v[70:71], v[2:3]
	v_mov_b64_e32 v[10:11], v[2:3]
	v_mov_b64_e32 v[14:15], v[2:3]
	v_mov_b64_e32 v[26:27], v[2:3]
	v_mov_b64_e32 v[30:31], v[2:3]
	v_mov_b64_e32 v[58:59], v[2:3]
	v_mov_b64_e32 v[62:63], v[2:3]
	v_mov_b64_e32 v[74:75], v[2:3]
	v_mov_b64_e32 v[78:79], v[2:3]
	v_mov_b64_e32 v[82:83], v[2:3]
	v_mov_b64_e32 v[86:87], v[2:3]
	v_mov_b64_e32 v[98:99], v[2:3]
	v_mov_b64_e32 v[102:103], v[2:3]
	v_mov_b64_e32 v[114:115], v[2:3]
	v_mov_b64_e32 v[118:119], v[2:3]
	v_mov_b64_e32 v[130:131], v[2:3]
	v_mov_b64_e32 v[134:135], v[2:3]
	v_mov_b64_e32 v[90:91], v[2:3]
	v_mov_b64_e32 v[94:95], v[2:3]
	v_mov_b64_e32 v[106:107], v[2:3]
	v_mov_b64_e32 v[110:111], v[2:3]
	v_mov_b64_e32 v[122:123], v[2:3]
	v_mov_b64_e32 v[126:127], v[2:3]
	v_mov_b64_e32 v[138:139], v[2:3]
	v_mov_b64_e32 v[142:143], v[2:3]
	s_mov_b32 s12, s0
	v_readlane_b32 s0, v253, 39
	v_mov_b32_e32 v43, v153
	v_mov_b32_e32 v45, v153
	s_mov_b32 s43, 0
	v_mov_b64_e32 v[4:5], v[0:1]
	v_mov_b64_e32 v[16:17], v[0:1]
	v_mov_b64_e32 v[20:21], v[0:1]
	v_mov_b64_e32 v[36:37], v[0:1]
	v_mov_b64_e32 v[52:53], v[0:1]
	v_mov_b64_e32 v[64:65], v[0:1]
	v_mov_b64_e32 v[68:69], v[0:1]
	v_mov_b64_e32 v[8:9], v[0:1]
	v_mov_b64_e32 v[12:13], v[0:1]
	v_mov_b64_e32 v[24:25], v[0:1]
	v_mov_b64_e32 v[28:29], v[0:1]
	v_mov_b64_e32 v[56:57], v[0:1]
	v_mov_b64_e32 v[60:61], v[0:1]
	v_mov_b64_e32 v[72:73], v[0:1]
	v_mov_b64_e32 v[76:77], v[0:1]
	v_mov_b64_e32 v[80:81], v[0:1]
	v_mov_b64_e32 v[84:85], v[0:1]
	v_mov_b64_e32 v[96:97], v[0:1]
	v_mov_b64_e32 v[100:101], v[0:1]
	v_mov_b64_e32 v[112:113], v[0:1]
	v_mov_b64_e32 v[116:117], v[0:1]
	v_mov_b64_e32 v[128:129], v[0:1]
	v_mov_b64_e32 v[132:133], v[0:1]
	v_mov_b64_e32 v[88:89], v[0:1]
	v_mov_b64_e32 v[92:93], v[0:1]
	v_mov_b64_e32 v[104:105], v[0:1]
	v_mov_b64_e32 v[108:109], v[0:1]
	v_mov_b64_e32 v[120:121], v[0:1]
	v_mov_b64_e32 v[124:125], v[0:1]
	v_mov_b64_e32 v[136:137], v[0:1]
	v_mov_b64_e32 v[140:141], v[0:1]
	s_mov_b32 s42, s0
	s_barrier
	v_readlane_b32 s1, v253, 40
	s_branch .LBB0_876
	s_nop 0
	s_nop 0
	s_nop 0
	s_nop 0
	s_nop 0
	s_nop 0
	s_nop 0
	s_nop 0
	s_nop 0
	s_nop 0
	s_nop 0
	s_nop 0
	s_nop 0
	s_nop 0
	s_nop 0
	s_nop 0
	s_nop 0
	s_nop 0
	s_nop 0
	s_nop 0
	s_nop 0
	s_nop 0
	s_nop 0
	s_nop 0
	s_nop 0
	s_nop 0
	s_nop 0
	s_nop 0
	s_nop 0
	s_nop 0
	s_nop 0
	s_nop 0
	s_nop 0
	s_nop 0
	s_nop 0
	s_nop 0
	s_nop 0
	s_nop 0
	s_nop 0
	s_nop 0
	s_nop 0
	s_nop 0
	s_nop 0
	s_nop 0
	s_nop 0
	s_nop 0
	s_nop 0
	s_nop 0
	s_nop 0
	s_nop 0
	s_nop 0
	s_nop 0
	s_nop 0
	s_nop 0
	s_nop 0
	s_nop 0
	s_nop 0
	s_nop 0
	s_nop 0
	s_nop 0
	s_nop 0
	s_nop 0
	s_nop 0
	s_nop 0
	s_nop 0
	s_nop 0
	s_nop 0
	s_nop 0
	s_nop 0
	s_nop 0
	s_nop 0
	s_nop 0
	s_nop 0
	s_nop 0
	s_nop 0
	s_nop 0
	s_nop 0
	s_nop 0
	s_nop 0
	s_nop 0
	s_nop 0
	s_nop 0
	s_nop 0
	s_nop 0
	s_nop 0
	s_nop 0
	s_nop 0
	s_nop 0
	s_nop 0
	s_nop 0
	s_nop 0
	s_nop 0
	s_nop 0
	s_nop 0
	s_nop 0
	s_nop 0
	s_nop 0
	s_nop 0
	s_nop 0
	s_nop 0
	s_nop 0
	s_nop 0
	s_nop 0
	s_nop 0
	s_nop 0
	s_nop 0
	s_nop 0
	s_nop 0
	s_nop 0
	s_nop 0
	s_nop 0
	s_nop 0
	s_nop 0
	s_nop 0
	s_nop 0
	s_nop 0
	s_nop 0
	s_nop 0
	s_nop 0
	s_nop 0
	s_nop 0
	s_nop 0
	s_nop 0
	s_nop 0
	s_nop 0
	s_nop 0
	s_nop 0
	s_nop 0

; __device__ __forceinline__ unsigned xb_ld(unsigned* p)              { return __hip_atomic_load(p, __ATOMIC_RELAXED, __HIP_MEMORY_SCOPE_AGENT); }
; __device__ __forceinline__ unsigned xb_add(unsigned* p, unsigned v) { return __hip_atomic_fetch_add(p, v, __ATOMIC_RELAXED, __HIP_MEMORY_SCOPE_AGENT); }
; #define XB_SPIN(cond, bar) do { unsigned _sp = 0; while (cond) { __builtin_amdgcn_s_sleep(1); \
;     if ((++_sp & 255u) == 0u) { if (xb_ld(&(bar)[XB_TMO])) break; if (_sp > XB_SPIN_CAP) { atomicAdd(&(bar)[XB_TMO], 1u); break; } } } } while (0)
; __device__ __forceinline__ void xcd_barrier(const XcdBarrier& b) {
;     ...
;             const unsigned og = xb_add(&bar[XB_TOP], 1u);
;             const unsigned tg = og / nx;
;             if (og + 1u == (tg + 1u) * nx) xb_add(&bar[XB_TOPGEN], 1u);
;             else XB_SPIN(xb_ld(&bar[XB_TOPGEN]) == tg, bar);
;             __builtin_amdgcn_fence(__ATOMIC_ACQUIRE, "agent");
.LBB0_942:
	s_or_b64 exec, exec, s[18:19]
	buffer_inv sc1
	s_waitcnt vmcnt(1)
	v_readfirstlane_b32 s13, v17
	v_cvt_f32_u32_e32 v17, v2
	v_sub_u32_e32 v18, 0, v2
	v_add_u32_e32 v3, s13, v3
	s_add_u32 s16, s10, 0x2e403500
	v_rcp_iflag_f32_e32 v17, v17
	s_addc_u32 s17, s11, 0
	s_mov_b64 s[20:21], -1
	v_mul_f32_e32 v17, 0x4f7ffffe, v17
	v_cvt_u32_f32_e32 v17, v17
	v_mul_lo_u32 v18, v18, v17
	v_mul_hi_u32 v18, v17, v18
	v_add_u32_e32 v17, v17, v18
	v_mul_hi_u32 v17, v3, v17
	v_mul_lo_u32 v18, v17, v2
	v_sub_u32_e32 v18, v3, v18
	v_cmp_ge_u32_e32 vcc, v18, v2
	v_add_u32_e32 v19, 1, v17
	v_add_u32_e32 v3, 1, v3
	v_cndmask_b32_e32 v17, v17, v19, vcc
	v_sub_u32_e32 v19, v18, v2
	v_cndmask_b32_e32 v18, v18, v19, vcc
	v_cmp_ge_u32_e32 vcc, v18, v2
	v_add_u32_e32 v18, 1, v17
	s_nop 0
	v_cndmask_b32_e32 v17, v17, v18, vcc
	v_mul_lo_u32 v18, v2, v17
	v_add_u32_e32 v2, v18, v2
	v_cmp_ne_u32_e32 vcc, v3, v2
	v_mov_b32_e32 v17, v2
	v_mov_b64_e32 v[2:3], s[16:17]
	s_and_saveexec_b64 s[18:19], vcc
	s_cbranch_execz .LBB0_954
	global_load_dword v2, v153, s[16:17] offset:-256 sc1
	s_mov_b64 s[24:25], 0
	s_waitcnt vmcnt(0)
	v_cmp_lt_u32_e32 vcc, v2, v17
	s_and_saveexec_b64 s[22:23], vcc
	s_cbranch_execz .LBB0_953
	s_add_u32 s20, s10, 0x2e400200
	s_addc_u32 s21, s11, 0
	s_mov_b32 s13, 1
	s_branch .LBB0_946

; __device__ __forceinline__ unsigned xb_ld(unsigned* p)              { return __hip_atomic_load(p, __ATOMIC_RELAXED, __HIP_MEMORY_SCOPE_AGENT); }
; #define XB_SPIN(cond, bar) do { unsigned _sp = 0; while (cond) { __builtin_amdgcn_s_sleep(1); \
;     if ((++_sp & 255u) == 0u) { if (xb_ld(&(bar)[XB_TMO])) break; if (_sp > XB_SPIN_CAP) { atomicAdd(&(bar)[XB_TMO], 1u); break; } } } } while (0)
; __device__ __forceinline__ void xcd_barrier(const XcdBarrier& b) {
;     ...
;             else XB_SPIN(xb_ld(&bar[XB_TOPGEN]) == tg, bar);
.LBB0_948:
	global_load_dword v2, v153, s[16:17] offset:-256 sc1
	s_add_i32 s13, s13, 1
	s_mov_b64 s[30:31], -1
	s_waitcnt vmcnt(0)
	v_cmp_ge_u32_e32 vcc, v2, v17
	s_orn2_b64 s[28:29], vcc, exec
	s_branch .LBB0_945

; __device__ __forceinline__ unsigned xb_add(unsigned* p, unsigned v) { return __hip_atomic_fetch_add(p, v, __ATOMIC_RELAXED, __HIP_MEMORY_SCOPE_AGENT); }
; __device__ __forceinline__ void xcd_barrier(const XcdBarrier& b) {
;     ...
;             __builtin_amdgcn_fence(__ATOMIC_ACQUIRE, "agent");
;             xb_add(&bar[XB_XGEN(b.x)], 1u);
;             asm volatile("s_waitcnt vmcnt(0)" ::: "memory");
.LBB0_956:
	s_or_b64 exec, exec, s[16:17]
	s_mov_b64 s[16:17], exec
	v_mbcnt_lo_u32_b32 v2, s16, 0
	v_mbcnt_hi_u32_b32 v2, s17, v2
	v_cmp_eq_u32_e32 vcc, 0, v2
	s_waitcnt vmcnt(0)
	s_and_saveexec_b64 s[18:19], vcc
	s_cbranch_execz .LBB0_958
	s_bcnt1_i32_b64 s13, s[16:17]
	v_mov_b32_e32 v2, s13
	v_mov_b32_e32 v3, 0x2000
	global_atomic_add v3, v2, s[14:15] offset:1024

; __device__ __forceinline__ unsigned xb_ld(unsigned* p)              { return __hip_atomic_load(p, __ATOMIC_RELAXED, __HIP_MEMORY_SCOPE_AGENT); }
; __device__ __forceinline__ unsigned xb_add(unsigned* p, unsigned v) { return __hip_atomic_fetch_add(p, v, __ATOMIC_RELAXED, __HIP_MEMORY_SCOPE_AGENT); }
; #define XB_SPIN(cond, bar) do { unsigned _sp = 0; while (cond) { __builtin_amdgcn_s_sleep(1); \
;     if ((++_sp & 255u) == 0u) { if (xb_ld(&(bar)[XB_TMO])) break; if (_sp > XB_SPIN_CAP) { atomicAdd(&(bar)[XB_TMO], 1u); break; } } } } while (0)
; __device__ __forceinline__ void xcd_barrier(const XcdBarrier& b) {
;     ...
;             const unsigned og = xb_add(&bar[XB_TOP], 1u);
;             const unsigned tg = og / nx;
;             if (og + 1u == (tg + 1u) * nx) xb_add(&bar[XB_TOPGEN], 1u);
;             else XB_SPIN(xb_ld(&bar[XB_TOPGEN]) == tg, bar);
;             __builtin_amdgcn_fence(__ATOMIC_ACQUIRE, "agent");
.LBB0_1003:
	s_or_b64 exec, exec, s[10:11]
	buffer_inv sc1
	s_waitcnt vmcnt(1)
	v_readfirstlane_b32 s8, v2
	v_cvt_f32_u32_e32 v2, v0
	v_sub_u32_e32 v3, 0, v0
	v_add_u32_e32 v1, s8, v1
	s_add_u32 s8, s2, 0x2e403500
	v_rcp_iflag_f32_e32 v2, v2
	s_addc_u32 s9, s3, 0
	s_mov_b64 s[12:13], -1
	v_mul_f32_e32 v2, 0x4f7ffffe, v2
	v_cvt_u32_f32_e32 v2, v2
	v_mul_lo_u32 v3, v3, v2
	v_mul_hi_u32 v3, v2, v3
	v_add_u32_e32 v2, v2, v3
	v_mul_hi_u32 v2, v1, v2
	v_mul_lo_u32 v3, v2, v0
	v_sub_u32_e32 v3, v1, v3
	v_cmp_ge_u32_e32 vcc, v3, v0
	v_add_u32_e32 v4, 1, v2
	v_add_u32_e32 v1, 1, v1
	v_cndmask_b32_e32 v2, v2, v4, vcc
	v_sub_u32_e32 v4, v3, v0
	v_cndmask_b32_e32 v3, v3, v4, vcc
	v_cmp_ge_u32_e32 vcc, v3, v0
	v_add_u32_e32 v3, 1, v2
	s_nop 0
	v_cndmask_b32_e32 v2, v2, v3, vcc
	v_mul_lo_u32 v3, v0, v2
	v_add_u32_e32 v0, v3, v0
	v_cmp_ne_u32_e32 vcc, v1, v0
	v_mov_b32_e32 v2, v0
	v_mov_b64_e32 v[0:1], s[8:9]
	s_and_saveexec_b64 s[10:11], vcc
	s_cbranch_execz .LBB0_1015
	global_load_dword v0, v153, s[8:9] offset:-256 sc1
	s_mov_b64 s[16:17], 0
	s_waitcnt vmcnt(0)
	v_cmp_lt_u32_e32 vcc, v0, v2
	s_and_saveexec_b64 s[14:15], vcc
	s_cbranch_execz .LBB0_1014
	s_add_u32 s12, s2, 0x2e400200
	s_addc_u32 s13, s3, 0
	s_mov_b32 s24, 1
	s_mov_b64 s[2:3], 0
	s_branch .LBB0_1007

; __device__ __forceinline__ unsigned xb_ld(unsigned* p)              { return __hip_atomic_load(p, __ATOMIC_RELAXED, __HIP_MEMORY_SCOPE_AGENT); }
; #define XB_SPIN(cond, bar) do { unsigned _sp = 0; while (cond) { __builtin_amdgcn_s_sleep(1); \
;     if ((++_sp & 255u) == 0u) { if (xb_ld(&(bar)[XB_TMO])) break; if (_sp > XB_SPIN_CAP) { atomicAdd(&(bar)[XB_TMO], 1u); break; } } } } while (0)
; __device__ __forceinline__ void xcd_barrier(const XcdBarrier& b) {
;     ...
;             else XB_SPIN(xb_ld(&bar[XB_TOPGEN]) == tg, bar);
.LBB0_1009:
	global_load_dword v0, v153, s[8:9] offset:-256 sc1
	s_add_i32 s24, s24, 1
	s_mov_b64 s[20:21], -1
	s_waitcnt vmcnt(0)
	v_cmp_ge_u32_e32 vcc, v0, v2
	s_orn2_b64 s[18:19], vcc, exec
	s_branch .LBB0_1006

; __device__ __forceinline__ unsigned xb_add(unsigned* p, unsigned v) { return __hip_atomic_fetch_add(p, v, __ATOMIC_RELAXED, __HIP_MEMORY_SCOPE_AGENT); }
; __device__ __forceinline__ void xcd_barrier(const XcdBarrier& b) {
;     ...
;             __builtin_amdgcn_fence(__ATOMIC_ACQUIRE, "agent");
;             xb_add(&bar[XB_XGEN(b.x)], 1u);
;             asm volatile("s_waitcnt vmcnt(0)" ::: "memory");
.LBB0_1017:
	s_or_b64 exec, exec, s[2:3]
	s_mov_b64 s[2:3], exec
	v_mbcnt_lo_u32_b32 v0, s2, 0
	v_mbcnt_hi_u32_b32 v0, s3, v0
	v_cmp_eq_u32_e32 vcc, 0, v0
	s_waitcnt vmcnt(0)
	s_and_saveexec_b64 s[8:9], vcc
	s_cbranch_execz .LBB0_1019
	s_bcnt1_i32_b64 s2, s[2:3]
	v_mov_b32_e32 v0, s2
	v_mov_b32_e32 v1, 0x2000
	global_atomic_add v1, v0, s[4:5] offset:1024

; #define PG8_STAGE(bufoff, gbase, voff) do { _Pragma("unroll") for (int _i = 0; _i < 2; ++_i) \
;         __builtin_amdgcn_global_load_lds((const unsigned*)((const char*)(gbase) + (voff)[_i]), (PG8_LAS unsigned*)(lds + (bufoff) + ldsw + _i * 8192), 16, 0, 0); } while (0)
; #define PG8_WAIT_V(n) asm volatile("s_waitcnt vmcnt(" #n ")" ::: "memory")
; #define PG8_BAR __builtin_amdgcn_s_barrier()
; template <class Epi, class Sched, bool ALIGN_EPI = false, bool SP2 = false>
; __device__ __forceinline__ void gemm_phase(PG8_LAS unsigned char* lds, const Gemm g, const Sched& S, const Epi& E) {
;     ...
;     const int aoff = lds_byte(wr * 64 + fr, fq * 8), boff = lds_byte(wc * 32 + fr, fq * 8);
;     ...
;         PG8_STAGE(PG8_SB(0, 0), cB, voffB); PG8_STAGE(PG8_SB(0, 1), cB + hstep, voffB); PG8_STAGE(PG8_SA(0, 0), cA, voffA); PG8_STAGE(PG8_SA(0, 1), cA + hstep, voffA);
;         if (wr == 1) PG8_BAR;
;         PG8_WAIT_V(2); PG8_BAR;
;         PG8_STAGE(PG8_SB(1, 0), cB + kstep, voffB); PG8_STAGE(PG8_SA(1, 0), cA + kstep, voffA); PG8_STAGE(PG8_SB(1, 1), cB + hstep + kstep, voffB);
;         PG8_WAIT_V(6); PG8_BAR;
.LBB0_1048:
	s_lshl_b32 s1, s1, 5
	s_and_b32 s41, s1, 0x60
	s_lshl_b32 s40, s4, 6
	s_lshl_b32 s18, s4, 13
	s_lshl_b32 s1, s41, 7
	s_add_u32 s4, s8, 0x26100000
	s_addc_u32 s5, s9, 0
	s_add_i32 m0, s36, 0x18000
	v_lshl_add_u64 v[6:7], v[6:7], 0, s[74:75]
	s_waitcnt vmcnt(2)
	s_barrier
	global_load_lds_dwordx4 v[6:7], off
	v_lshl_add_u64 v[4:5], v[4:5], 0, s[74:75]
	s_add_i32 m0, s36, 0x1a000
	s_add_i32 s42, s36, 0x8000
	s_add_i32 s43, s36, 0xa000
	global_load_lds_dwordx4 v[4:5], off
	v_lshl_add_u64 v[0:1], v[0:1], 0, s[74:75]
	s_mov_b32 m0, s42
	s_add_u32 s16, s28, 0x80080
	global_load_lds_dwordx4 v[0:1], off
	v_lshl_add_u64 v[0:1], v[2:3], 0, s[74:75]
	s_mov_b32 m0, s43
	s_addc_u32 s17, s29, 0
	global_load_lds_dwordx4 v[0:1], off
	s_add_i32 m0, s36, 0x1c000
	v_lshl_add_u64 v[0:1], s[16:17], 0, v[152:153]
	global_load_lds_dwordx4 v[0:1], off
	v_lshl_add_u64 v[0:1], s[16:17], 0, v[128:129]
	s_add_i32 m0, s36, 0x1e000
	v_bfe_u32 v143, v8, 4, 2
	global_load_lds_dwordx4 v[0:1], off
	v_and_b32_e32 v142, 15, v8
	v_lshlrev_b32_e32 v0, 4, v143
	v_lshlrev_b32_e32 v1, 2, v8
	v_lshl_or_b32 v0, v142, 6, v0
	v_and_b32_e32 v1, 32, v1
	v_bitop3_b32 v2, v0, s18, v1 bitop3:0xde
	v_bitop3_b32 v144, v0, s1, v1 bitop3:0xde
	v_lshlrev_b32_e32 v0, 15, v13
	v_and_b32_e32 v0, 0xffff0000, v0
	v_lshl_add_u32 v0, v12, 12, v0
	v_and_b32_e32 v1, 1, v13
	v_lshl_or_b32 v0, v1, 6, v0
	v_lshl_add_u32 v134, v14, 1, v0
	v_lshlrev_b32_e32 v0, 15, v9
	v_and_b32_e32 v0, 0xffff0000, v0
	s_waitcnt vmcnt(6)
	v_lshl_add_u32 v0, v10, 12, v0
	v_and_b32_e32 v1, 1, v9
	s_cmpk_lt_u32 s0, 0x100
	v_lshl_or_b32 v0, v1, 6, v0
	v_readlane_b32 s0, v253, 33
	s_cselect_b64 s[16:17], -1, 0
	v_mov_b32_e32 v135, v153
	v_lshl_add_u32 v136, v11, 1, v0
	v_mov_b32_e32 v137, v153
	s_mov_b32 s44, 0
	v_add_u32_e32 v145, 0, v2
	v_readlane_b32 s45, v253, 32
	s_mov_b32 s46, s0
	s_barrier
	v_readlane_b32 s1, v253, 34
	s_branch .LBB0_1051
	s_nop 0
	s_nop 0
	s_nop 0
	s_nop 0
	s_nop 0
	s_nop 0
	s_nop 0
	s_nop 0
	s_nop 0
	s_nop 0
	s_nop 0
	s_nop 0
	s_nop 0
	s_nop 0
	s_nop 0
	s_nop 0
	s_nop 0
	s_nop 0
	s_nop 0
	s_nop 0
	s_nop 0
	s_nop 0
	s_nop 0
	s_nop 0
	s_nop 0
	s_nop 0
	s_nop 0
	s_nop 0
	s_nop 0
	s_nop 0
	s_nop 0
	s_nop 0
	s_nop 0
	s_nop 0
	s_nop 0
	s_nop 0
	s_nop 0
	s_nop 0
	s_nop 0
	s_nop 0
	s_nop 0
	s_nop 0
	s_nop 0
	s_nop 0
	s_nop 0
	s_nop 0
	s_nop 0
	s_nop 0
	s_nop 0
	s_nop 0
	s_nop 0
	s_nop 0
	s_nop 0
	s_nop 0
	s_nop 0
	s_nop 0
	s_nop 0
	s_nop 0
	s_nop 0
	s_nop 0
	s_nop 0
	s_nop 0
	s_nop 0
	s_nop 0
	s_nop 0
	s_nop 0
	s_nop 0
	s_nop 0
	s_nop 0
	s_nop 0
	s_nop 0
	s_nop 0
	s_nop 0
	s_nop 0
	s_nop 0
	s_nop 0
	s_nop 0
	s_nop 0
	s_nop 0
	s_nop 0
	s_nop 0
	s_nop 0
	s_nop 0
	s_nop 0
	s_nop 0
	s_nop 0
	s_nop 0
	s_nop 0
	s_nop 0
	s_nop 0
	s_nop 0
	s_nop 0
	s_nop 0
	s_nop 0
	s_nop 0
	s_nop 0
	s_nop 0
	s_nop 0
	s_nop 0
	s_nop 0
	s_nop 0
	s_nop 0
	s_nop 0
	s_nop 0
	s_nop 0
	s_nop 0
	s_nop 0
	s_nop 0
	s_nop 0
	s_nop 0
	s_nop 0
	s_nop 0
	s_nop 0
	s_nop 0
	s_nop 0
	s_nop 0
	s_nop 0
	s_nop 0
	s_nop 0
	s_nop 0
	s_nop 0
	s_nop 0
	s_nop 0
	s_nop 0
	s_nop 0
	s_nop 0
	s_nop 0
	s_nop 0
	s_nop 0
	s_nop 0
	s_nop 0
	s_nop 0
	s_nop 0
	s_nop 0
	s_nop 0
	s_nop 0
	s_nop 0
	s_nop 0
	s_nop 0
	s_nop 0
	s_nop 0
	s_nop 0
	s_nop 0
	s_nop 0
	s_nop 0
	s_nop 0
	s_nop 0
	s_nop 0
	s_nop 0
	s_nop 0
	s_nop 0
	s_nop 0
	s_nop 0
	s_nop 0
	s_nop 0
	s_nop 0
	s_nop 0
	s_nop 0
	s_nop 0
	s_nop 0
	s_nop 0
	s_nop 0
	s_nop 0
	s_nop 0
	s_nop 0
	s_nop 0
	s_nop 0
	s_nop 0
	s_nop 0
	s_nop 0
	s_nop 0
	s_nop 0
	s_nop 0
	s_nop 0
	s_nop 0
	s_nop 0
	s_nop 0
	s_nop 0
	s_nop 0
	s_nop 0
	s_nop 0
	s_nop 0
	s_nop 0
	s_nop 0
	s_nop 0
	s_nop 0
	s_nop 0

; #define PG8_STAGE(bufoff, gbase, voff) do { _Pragma("unroll") for (int _i = 0; _i < 2; ++_i) \
;         __builtin_amdgcn_global_load_lds((const unsigned*)((const char*)(gbase) + (voff)[_i]), (PG8_LAS unsigned*)(lds + (bufoff) + ldsw + _i * 8192), 16, 0, 0); } while (0)
; #define PG8_WAIT_V(n) asm volatile("s_waitcnt vmcnt(" #n ")" ::: "memory")
; #define PG8_BAR __builtin_amdgcn_s_barrier()
; template <class Epi, class Sched, bool ALIGN_EPI = false, bool SP2 = false>
; __device__ __forceinline__ void gemm_phase(PG8_LAS unsigned char* lds, const Gemm g, const Sched& S, const Epi& E) {
;     ...
;     f32x4 acc[2][2][4][2];
; #pragma unroll
;     for (int a = 0; a < 2; ++a)
; #pragma unroll
;         for (int b = 0; b < 2; ++b)
; #pragma unroll
;             for (int m = 0; m < 4; ++m)
; #pragma unroll
;                 for (int n = 0; n < 2; ++n) acc[a][b][m][n] = (f32x4){0.f, 0.f, 0.f, 0.f};
;     ...
;         PG8_STAGE(PG8_SB(0, 0), cB, voffB); PG8_STAGE(PG8_SB(0, 1), cB + hstep, voffB); PG8_STAGE(PG8_SA(0, 0), cA, voffA); PG8_STAGE(PG8_SA(0, 1), cA + hstep, voffA);
;         if (wr == 1) PG8_BAR;
;         PG8_WAIT_V(2); PG8_BAR;
;         PG8_STAGE(PG8_SB(1, 0), cB + kstep, voffB); PG8_STAGE(PG8_SA(1, 0), cA + kstep, voffA); PG8_STAGE(PG8_SB(1, 1), cB + hstep + kstep, voffB);
;         PG8_WAIT_V(6); PG8_BAR;
.LBB0_1159:
	v_lshl_add_u64 v[6:7], s[22:23], 0, v[152:153]
	v_mov_b32_e32 v33, v153
	v_lshl_add_u64 v[8:9], s[22:23], 0, v[32:33]
	v_mov_b32_e32 v41, v153
	s_and_b32 s34, s5, 3
	s_add_i32 m0, s35, 0x18000
	v_lshl_add_u64 v[6:7], v[6:7], 0, s[74:75]
	v_lshl_add_u64 v[10:11], s[2:3], 0, v[40:41]
	v_mov_b32_e32 v35, v153
	s_lshl_b32 s36, s4, 6
	s_lshl_b32 s4, s4, 13
	s_lshl_b32 s5, s34, 12
	s_waitcnt vmcnt(2)
	s_barrier
	global_load_lds_dwordx4 v[6:7], off
	v_lshl_add_u64 v[6:7], v[8:9], 0, s[74:75]
	s_add_i32 m0, s35, 0x1a000
	s_add_i32 s40, s35, 0x8000
	s_add_i32 s41, s35, 0xa000
	v_lshl_add_u64 v[12:13], s[2:3], 0, v[34:35]
	global_load_lds_dwordx4 v[6:7], off
	v_lshl_add_u64 v[6:7], v[10:11], 0, s[74:75]
	s_mov_b32 m0, s40
	s_add_u32 s0, s22, 0x200080
	global_load_lds_dwordx4 v[6:7], off
	v_lshl_add_u64 v[6:7], v[12:13], 0, s[74:75]
	s_mov_b32 m0, s41
	s_addc_u32 s1, s23, 0
	global_load_lds_dwordx4 v[6:7], off
	s_add_i32 m0, s35, 0x1c000
	v_lshl_add_u64 v[6:7], s[0:1], 0, v[152:153]
	global_load_lds_dwordx4 v[6:7], off
	v_lshl_add_u64 v[6:7], s[0:1], 0, v[32:33]
	s_add_i32 m0, s35, 0x1e000
	v_and_b32_e32 v144, 15, v234
	global_load_lds_dwordx4 v[6:7], off
	v_and_b32_e32 v6, 48, v234
	v_lshlrev_b32_e32 v7, 2, v234
	v_lshl_or_b32 v6, v144, 6, v6
	v_and_b32_e32 v7, 32, v7
	v_bitop3_b32 v8, v6, s4, v7 bitop3:0xde
	v_bitop3_b32 v50, v6, s5, v7 bitop3:0xde
	v_lshlrev_b32_e32 v6, 17, v4
	v_and_b32_e32 v6, 0xfffc0000, v6
	v_lshl_add_u32 v3, v3, 14, v6
	v_and_b32_e32 v4, 1, v4
	v_lshl_or_b32 v3, v4, 6, v3
	v_lshl_add_u32 v42, v5, 1, v3
	v_lshlrev_b32_e32 v3, 17, v0
	v_and_b32_e32 v3, 0xfffc0000, v3
	v_lshl_add_u32 v1, v1, 14, v3
	v_and_b32_e32 v0, 1, v0
	v_lshl_or_b32 v0, v0, 6, v1
	s_waitcnt vmcnt(6)
	v_lshl_add_u32 v44, v2, 1, v0
	v_mov_b32_e32 v2, v153
	v_mov_b32_e32 v3, v153
	v_readlane_b32 s0, v253, 27
	v_mov_b32_e32 v0, v153
	v_mov_b32_e32 v1, v153
	v_add_u32_e32 v51, 0, v8
	v_mov_b64_e32 v[6:7], v[2:3]
	v_mov_b64_e32 v[18:19], v[2:3]
	v_mov_b64_e32 v[22:23], v[2:3]
	v_mov_b64_e32 v[38:39], v[2:3]
	v_mov_b64_e32 v[54:55], v[2:3]
	v_mov_b64_e32 v[66:67], v[2:3]
	v_mov_b64_e32 v[70:71], v[2:3]
	v_mov_b64_e32 v[10:11], v[2:3]
	v_mov_b64_e32 v[14:15], v[2:3]
	v_mov_b64_e32 v[26:27], v[2:3]
	v_mov_b64_e32 v[30:31], v[2:3]
	v_mov_b64_e32 v[58:59], v[2:3]
	v_mov_b64_e32 v[62:63], v[2:3]
	v_mov_b64_e32 v[74:75], v[2:3]
	v_mov_b64_e32 v[78:79], v[2:3]
	v_mov_b64_e32 v[82:83], v[2:3]
	v_mov_b64_e32 v[86:87], v[2:3]
	v_mov_b64_e32 v[98:99], v[2:3]
	v_mov_b64_e32 v[102:103], v[2:3]
	v_mov_b64_e32 v[114:115], v[2:3]
	v_mov_b64_e32 v[118:119], v[2:3]
	v_mov_b64_e32 v[130:131], v[2:3]
	v_mov_b64_e32 v[134:135], v[2:3]
	v_mov_b64_e32 v[90:91], v[2:3]
	v_mov_b64_e32 v[94:95], v[2:3]
	v_mov_b64_e32 v[106:107], v[2:3]
	v_mov_b64_e32 v[110:111], v[2:3]
	v_mov_b64_e32 v[122:123], v[2:3]
	v_mov_b64_e32 v[126:127], v[2:3]
	v_mov_b64_e32 v[138:139], v[2:3]
	v_mov_b64_e32 v[142:143], v[2:3]
	s_mov_b32 s6, s0
	v_readlane_b32 s0, v253, 39
	v_mov_b32_e32 v43, v153
	v_mov_b32_e32 v45, v153
	s_mov_b32 s43, 0
	v_mov_b64_e32 v[4:5], v[0:1]
	v_mov_b64_e32 v[16:17], v[0:1]
	v_mov_b64_e32 v[20:21], v[0:1]
	v_mov_b64_e32 v[36:37], v[0:1]
	v_mov_b64_e32 v[52:53], v[0:1]
	v_mov_b64_e32 v[64:65], v[0:1]
	v_mov_b64_e32 v[68:69], v[0:1]
	v_mov_b64_e32 v[8:9], v[0:1]
	v_mov_b64_e32 v[12:13], v[0:1]
	v_mov_b64_e32 v[24:25], v[0:1]
	v_mov_b64_e32 v[28:29], v[0:1]
	v_mov_b64_e32 v[56:57], v[0:1]
	v_mov_b64_e32 v[60:61], v[0:1]
	v_mov_b64_e32 v[72:73], v[0:1]
	v_mov_b64_e32 v[76:77], v[0:1]
	v_mov_b64_e32 v[80:81], v[0:1]
	v_mov_b64_e32 v[84:85], v[0:1]
	v_mov_b64_e32 v[96:97], v[0:1]
	v_mov_b64_e32 v[100:101], v[0:1]
	v_mov_b64_e32 v[112:113], v[0:1]
	v_mov_b64_e32 v[116:117], v[0:1]
	v_mov_b64_e32 v[128:129], v[0:1]
	v_mov_b64_e32 v[132:133], v[0:1]
	v_mov_b64_e32 v[88:89], v[0:1]
	v_mov_b64_e32 v[92:93], v[0:1]
	v_mov_b64_e32 v[104:105], v[0:1]
	v_mov_b64_e32 v[108:109], v[0:1]
	v_mov_b64_e32 v[120:121], v[0:1]
	v_mov_b64_e32 v[124:125], v[0:1]
	v_mov_b64_e32 v[136:137], v[0:1]
	v_mov_b64_e32 v[140:141], v[0:1]
	s_mov_b32 s42, s0
	s_barrier
	v_readlane_b32 s1, v253, 40
	s_branch .LBB0_1162
	s_nop 0
	s_nop 0
	s_nop 0
	s_nop 0
	s_nop 0
	s_nop 0
	s_nop 0
	s_nop 0
	s_nop 0
	s_nop 0
	s_nop 0
	s_nop 0
	s_nop 0
	s_nop 0
	s_nop 0
	s_nop 0
	s_nop 0
	s_nop 0
	s_nop 0
	s_nop 0
	s_nop 0
	s_nop 0
	s_nop 0
	s_nop 0
	s_nop 0
	s_nop 0
	s_nop 0
	s_nop 0
	s_nop 0
	s_nop 0
	s_nop 0
	s_nop 0
	s_nop 0
	s_nop 0
	s_nop 0
	s_nop 0
	s_nop 0
	s_nop 0
	s_nop 0
	s_nop 0
	s_nop 0
	s_nop 0
	s_nop 0
	s_nop 0
	s_nop 0
	s_nop 0
	s_nop 0
	s_nop 0
	s_nop 0
	s_nop 0
	s_nop 0
	s_nop 0
	s_nop 0
	s_nop 0
	s_nop 0
	s_nop 0
	s_nop 0
	s_nop 0
	s_nop 0
	s_nop 0
	s_nop 0
	s_nop 0
	s_nop 0
	s_nop 0
	s_nop 0
	s_nop 0
	s_nop 0
	s_nop 0
	s_nop 0
	s_nop 0
	s_nop 0
	s_nop 0
	s_nop 0
	s_nop 0
	s_nop 0
	s_nop 0
	s_nop 0
	s_nop 0
	s_nop 0
	s_nop 0
	s_nop 0
	s_nop 0
	s_nop 0
	s_nop 0
	s_nop 0
	s_nop 0
	s_nop 0
	s_nop 0
	s_nop 0
	s_nop 0
	s_nop 0
	s_nop 0
	s_nop 0
	s_nop 0
	s_nop 0
	s_nop 0
	s_nop 0
	s_nop 0
	s_nop 0
	s_nop 0
	s_nop 0
	s_nop 0
	s_nop 0
	s_nop 0
	s_nop 0
	s_nop 0
	s_nop 0
	s_nop 0
	s_nop 0
	s_nop 0
	s_nop 0
	s_nop 0
	s_nop 0
	s_nop 0
	s_nop 0
	s_nop 0
	s_nop 0
	s_nop 0
	s_nop 0
	s_nop 0
	s_nop 0
	s_nop 0
	s_nop 0
	s_nop 0
	s_nop 0
	s_nop 0
	s_nop 0
	s_nop 0
	s_nop 0

; __device__ __forceinline__ unsigned xb_ld(unsigned* p)              { return __hip_atomic_load(p, __ATOMIC_RELAXED, __HIP_MEMORY_SCOPE_AGENT); }
; __device__ __forceinline__ unsigned xb_add(unsigned* p, unsigned v) { return __hip_atomic_fetch_add(p, v, __ATOMIC_RELAXED, __HIP_MEMORY_SCOPE_AGENT); }
; #define XB_SPIN(cond, bar) do { unsigned _sp = 0; while (cond) { __builtin_amdgcn_s_sleep(1); \
;     if ((++_sp & 255u) == 0u) { if (xb_ld(&(bar)[XB_TMO])) break; if (_sp > XB_SPIN_CAP) { atomicAdd(&(bar)[XB_TMO], 1u); break; } } } } while (0)
; __device__ __forceinline__ void xcd_barrier(const XcdBarrier& b) {
;     ...
;             const unsigned og = xb_add(&bar[XB_TOP], 1u);
;             const unsigned tg = og / nx;
;             if (og + 1u == (tg + 1u) * nx) xb_add(&bar[XB_TOPGEN], 1u);
;             else XB_SPIN(xb_ld(&bar[XB_TOPGEN]) == tg, bar);
;             __builtin_amdgcn_fence(__ATOMIC_ACQUIRE, "agent");
.LBB0_1227:
	s_or_b64 exec, exec, s[16:17]
	buffer_inv sc1
	s_waitcnt vmcnt(1)
	v_readfirstlane_b32 s7, v5
	v_cvt_f32_u32_e32 v5, v2
	v_sub_u32_e32 v6, 0, v2
	v_add_u32_e32 v3, s7, v3
	s_add_u32 s14, s12, 0x2e403500
	v_rcp_iflag_f32_e32 v5, v5
	s_addc_u32 s15, s13, 0
	s_mov_b64 s[18:19], -1
	v_mul_f32_e32 v5, 0x4f7ffffe, v5
	v_cvt_u32_f32_e32 v5, v5
	v_mul_lo_u32 v6, v6, v5
	v_mul_hi_u32 v6, v5, v6
	v_add_u32_e32 v5, v5, v6
	v_mul_hi_u32 v5, v3, v5
	v_mul_lo_u32 v6, v5, v2
	v_sub_u32_e32 v6, v3, v6
	v_cmp_ge_u32_e32 vcc, v6, v2
	v_add_u32_e32 v7, 1, v5
	v_add_u32_e32 v3, 1, v3
	v_cndmask_b32_e32 v5, v5, v7, vcc
	v_sub_u32_e32 v7, v6, v2
	v_cndmask_b32_e32 v6, v6, v7, vcc
	v_cmp_ge_u32_e32 vcc, v6, v2
	v_add_u32_e32 v6, 1, v5
	s_nop 0
	v_cndmask_b32_e32 v5, v5, v6, vcc
	v_mul_lo_u32 v6, v2, v5
	v_add_u32_e32 v2, v6, v2
	v_cmp_ne_u32_e32 vcc, v3, v2
	v_mov_b32_e32 v5, v2
	v_mov_b64_e32 v[2:3], s[14:15]
	s_and_saveexec_b64 s[16:17], vcc
	s_cbranch_execz .LBB0_1239
	global_load_dword v2, v153, s[14:15] offset:-256 sc1
	s_mov_b64 s[22:23], 0
	s_waitcnt vmcnt(0)
	v_cmp_lt_u32_e32 vcc, v2, v5
	s_and_saveexec_b64 s[20:21], vcc
	s_cbranch_execz .LBB0_1238
	s_add_u32 s18, s12, 0x2e400200
	s_addc_u32 s19, s13, 0
	s_mov_b32 s7, 1
	s_branch .LBB0_1231

; __device__ __forceinline__ unsigned xb_ld(unsigned* p)              { return __hip_atomic_load(p, __ATOMIC_RELAXED, __HIP_MEMORY_SCOPE_AGENT); }
; #define XB_SPIN(cond, bar) do { unsigned _sp = 0; while (cond) { __builtin_amdgcn_s_sleep(1); \
;     if ((++_sp & 255u) == 0u) { if (xb_ld(&(bar)[XB_TMO])) break; if (_sp > XB_SPIN_CAP) { atomicAdd(&(bar)[XB_TMO], 1u); break; } } } } while (0)
; __device__ __forceinline__ void xcd_barrier(const XcdBarrier& b) {
;     ...
;             else XB_SPIN(xb_ld(&bar[XB_TOPGEN]) == tg, bar);
.LBB0_1233:
	global_load_dword v2, v153, s[14:15] offset:-256 sc1
	s_add_i32 s7, s7, 1
	s_mov_b64 s[28:29], -1
	s_waitcnt vmcnt(0)
	v_cmp_ge_u32_e32 vcc, v2, v5
	s_orn2_b64 s[26:27], vcc, exec
	s_branch .LBB0_1230

; __device__ __forceinline__ unsigned xb_add(unsigned* p, unsigned v) { return __hip_atomic_fetch_add(p, v, __ATOMIC_RELAXED, __HIP_MEMORY_SCOPE_AGENT); }
; __device__ __forceinline__ void xcd_barrier(const XcdBarrier& b) {
;     ...
;             __builtin_amdgcn_fence(__ATOMIC_ACQUIRE, "agent");
;             xb_add(&bar[XB_XGEN(b.x)], 1u);
;             asm volatile("s_waitcnt vmcnt(0)" ::: "memory");
.LBB0_1241:
	s_or_b64 exec, exec, s[14:15]
	s_mov_b64 s[14:15], exec
	v_mbcnt_lo_u32_b32 v2, s14, 0
	v_mbcnt_hi_u32_b32 v2, s15, v2
	v_cmp_eq_u32_e32 vcc, 0, v2
	s_waitcnt vmcnt(0)
	s_and_saveexec_b64 s[16:17], vcc
	s_cbranch_execz .LBB0_1243
	s_bcnt1_i32_b64 s7, s[14:15]
	v_mov_b32_e32 v2, s7
	v_mov_b32_e32 v3, 0x2000
	global_atomic_add v3, v2, s[8:9] offset:1024
